# peeled last two K steps of the pipelined GEMM loops without the redundant clamped DMA re-loads (epilogue vmcnt(0) no longer waits on them)
# speedup vs baseline: 1.0235x; 1.0038x over previous
; #define LAS __attribute__((address_space(3)))
; DI f32x16 mfma32(bf16x8 a, bf16x8 b, f32x16 c) { return __builtin_amdgcn_mfma_f32_32x32x16_bf16(a, b, c, 0, 0, 0); }
;     ...
;   for (int kt = 0; kt < nk; ++kt) {
;     const int kn = (kt + 2 < nk) ? (kt + 2) : (nk - 1);
;     const LAS char* cur = lds + s0;
;     bf16x8 af[2][2], bfr[2][4];
; #pragma unroll
;     for (int kk = 0; kk < 2; ++kk) {
;       const int xo = kk ? x1 : x0;
;       af[kk][0] = *(const LAS bf16x8*)(cur + a_rd + xo);
;       bfr[kk][0] = *(const LAS bf16x8*)(cur + b_rd + xo);
;       bfr[kk][1] = *(const LAS bf16x8*)(cur + b_rd + 2048 + xo);
;       af[kk][1] = *(const LAS bf16x8*)(cur + a_rd + 2048 + xo);
;       bfr[kk][2] = *(const LAS bf16x8*)(cur + b_rd + 4096 + xo);
;       bfr[kk][3] = *(const LAS bf16x8*)(cur + b_rd + 6144 + xo);
;     }
;     DMA_STEP_(kn, s2);
; #pragma unroll
;     for (int kk = 0; kk < 2; ++kk) {
;       acc[0][0] = mfma32(bfr[kk][0], af[kk][0], acc[0][0]); acc[0][1] = mfma32(bfr[kk][1], af[kk][0], acc[0][1]);
;       acc[1][0] = mfma32(bfr[kk][0], af[kk][1], acc[1][0]); acc[1][1] = mfma32(bfr[kk][1], af[kk][1], acc[1][1]);
;       acc[0][2] = mfma32(bfr[kk][2], af[kk][0], acc[0][2]); acc[0][3] = mfma32(bfr[kk][3], af[kk][0], acc[0][3]);
;       acc[1][2] = mfma32(bfr[kk][2], af[kk][1], acc[1][2]); acc[1][3] = mfma32(bfr[kk][3], af[kk][1], acc[1][3]);
;     }
;     __builtin_amdgcn_sched_group_barrier(0x100, 12, 0);
;     __builtin_amdgcn_sched_group_barrier(0x010, 6, 0);
;     __builtin_amdgcn_sched_group_barrier(0x008, 16, 0);
;     asm volatile("s_waitcnt vmcnt(6) lgkmcnt(0)" ::: "memory");
;     __builtin_amdgcn_s_barrier();
;     asm volatile("" ::: "memory");
;     s0 = (s0 == 2 * STG) ? 0 : s0 + STG;
;     s2 = (s2 == 2 * STG) ? 0 : s2 + STG;
;   }
.LBB0_21:
	s_add_i32 s11, s42, 16
	s_mov_b32 s10, s40
	v_add_u32_e32 v142, s11, v219
	v_add_u32_e32 v150, s11, v218
	s_min_u32 s10, s10, 29
	v_add_u32_e32 v142, v142, v220
	v_add_u32_e32 v150, v150, v220
	s_lshl_b32 s70, s10, 6
	ds_read_b128 v[138:141], v142
	ds_read_b128 v[162:165], v150 offset:8192
	ds_read_b128 v[166:169], v150 offset:10240
	ds_read_b128 v[142:145], v142 offset:2048
	ds_read_b128 v[146:149], v150 offset:12288
	ds_read_b128 v[150:153], v150 offset:14336
	v_lshl_add_u64 v[222:223], v[192:193], 0, s[70:71]
	s_add_i32 s10, s13, s41
	v_lshl_add_u64 v[224:225], v[222:223], 0, s[24:25]
	s_mov_b32 m0, s10
	v_lshl_add_u64 v[222:223], v[222:223], 0, s[38:39]
	s_mul_i32 s100, s70, 0x400
	s_waitcnt lgkmcnt(6)
	v_mfma_f32_32x32x16_bf16 v[114:129], v[182:185], v[154:157], v[114:129]
	global_load_lds_dwordx4 v[224:225], off
	s_add_i32 m0, s10, 0x400
	v_mfma_f32_32x32x16_bf16 v[98:113], v[178:181], v[154:157], v[98:113]
	global_load_lds_dwordx4 v[222:223], off
	v_lshl_add_u64 v[224:225], v[194:195], 0, s[100:101]
	s_add_i32 s10, s29, s41
	s_add_i32 m0, s10, 0x2000
	v_mfma_f32_32x32x16_bf16 v[66:81], v[182:185], v[158:161], v[66:81]
	global_load_lds_dwordx4 v[224:225], off
	v_mfma_f32_32x32x16_bf16 v[34:49], v[178:181], v[158:161], v[34:49]
	global_load_lds_dwordx4 v[224:225], off offset:1024
	v_mfma_f32_32x32x16_bf16 v[82:97], v[174:177], v[154:157], v[82:97]
	global_load_lds_dwordx4 v[224:225], off offset:2048
	v_mfma_f32_32x32x16_bf16 v[50:65], v[170:173], v[154:157], v[50:65]
	global_load_lds_dwordx4 v[224:225], off offset:3072
	v_mfma_f32_32x32x16_bf16 v[18:33], v[174:177], v[158:161], v[18:33]
	s_add_i32 s10, s42, 0x6000
	s_cmpk_lg_u32 s42, 0xc000
	s_cselect_b32 s42, s10, 0
	s_add_i32 s10, s41, 0x6000
	s_cmpk_lg_u32 s41, 0xc000
	s_cselect_b32 s41, s10, 0
	v_mfma_f32_32x32x16_bf16 v[2:17], v[170:173], v[158:161], v[2:17]
	s_add_i32 s11, s42, 16
	s_waitcnt vmcnt(6) lgkmcnt(0)
	s_barrier
	v_add_u32_e32 v158, s11, v219
	v_add_u32_e32 v170, s11, v218
	v_add_u32_e32 v158, v158, v0
	v_add_u32_e32 v170, v170, v0
	ds_read_b128 v[154:157], v158
	ds_read_b128 v[182:185], v170 offset:8192
	ds_read_b128 v[178:181], v170 offset:10240
	ds_read_b128 v[158:161], v158 offset:2048
	ds_read_b128 v[174:177], v170 offset:12288
	ds_read_b128 v[170:173], v170 offset:14336
	v_mfma_f32_32x32x16_bf16 v[114:129], v[162:165], v[138:141], v[114:129]
	v_mfma_f32_32x32x16_bf16 v[98:113], v[166:169], v[138:141], v[98:113]
	v_mfma_f32_32x32x16_bf16 v[66:81], v[162:165], v[142:145], v[66:81]
	v_mfma_f32_32x32x16_bf16 v[34:49], v[166:169], v[142:145], v[34:49]
	v_mfma_f32_32x32x16_bf16 v[82:97], v[146:149], v[138:141], v[82:97]
	v_mfma_f32_32x32x16_bf16 v[50:65], v[150:153], v[138:141], v[50:65]
	v_mfma_f32_32x32x16_bf16 v[18:33], v[146:149], v[142:145], v[18:33]
	v_mfma_f32_32x32x16_bf16 v[2:17], v[150:153], v[142:145], v[2:17]
	s_add_i32 s11, s42, 16
	s_add_i32 s10, s40, 1
	v_add_u32_e32 v142, s11, v219
	v_add_u32_e32 v150, s11, v218
	s_min_u32 s10, s10, 29
	v_add_u32_e32 v142, v142, v220
	v_add_u32_e32 v150, v150, v220
	s_lshl_b32 s70, s10, 6
	ds_read_b128 v[138:141], v142
	ds_read_b128 v[162:165], v150 offset:8192
	ds_read_b128 v[166:169], v150 offset:10240
	ds_read_b128 v[142:145], v142 offset:2048
	ds_read_b128 v[146:149], v150 offset:12288
	ds_read_b128 v[150:153], v150 offset:14336
	v_lshl_add_u64 v[222:223], v[192:193], 0, s[70:71]
	s_add_i32 s10, s13, s41
	v_lshl_add_u64 v[224:225], v[222:223], 0, s[24:25]
	s_mov_b32 m0, s10
	v_lshl_add_u64 v[222:223], v[222:223], 0, s[38:39]
	s_mul_i32 s100, s70, 0x400
	s_waitcnt lgkmcnt(6)
	v_mfma_f32_32x32x16_bf16 v[114:129], v[182:185], v[154:157], v[114:129]
	global_load_lds_dwordx4 v[224:225], off
	s_add_i32 m0, s10, 0x400
	v_mfma_f32_32x32x16_bf16 v[98:113], v[178:181], v[154:157], v[98:113]
	global_load_lds_dwordx4 v[222:223], off
	v_lshl_add_u64 v[224:225], v[194:195], 0, s[100:101]
	s_add_i32 s10, s29, s41
	s_add_i32 m0, s10, 0x2000
	v_mfma_f32_32x32x16_bf16 v[66:81], v[182:185], v[158:161], v[66:81]
	global_load_lds_dwordx4 v[224:225], off
	v_mfma_f32_32x32x16_bf16 v[34:49], v[178:181], v[158:161], v[34:49]
	global_load_lds_dwordx4 v[224:225], off offset:1024
	v_mfma_f32_32x32x16_bf16 v[82:97], v[174:177], v[154:157], v[82:97]
	global_load_lds_dwordx4 v[224:225], off offset:2048
	v_mfma_f32_32x32x16_bf16 v[50:65], v[170:173], v[154:157], v[50:65]
	global_load_lds_dwordx4 v[224:225], off offset:3072
	v_mfma_f32_32x32x16_bf16 v[18:33], v[174:177], v[158:161], v[18:33]
	s_add_i32 s10, s42, 0x6000
	s_cmpk_lg_u32 s42, 0xc000
	s_cselect_b32 s42, s10, 0
	s_add_i32 s10, s41, 0x6000
	s_cmpk_lg_u32 s41, 0xc000
	s_cselect_b32 s41, s10, 0
	v_mfma_f32_32x32x16_bf16 v[2:17], v[170:173], v[158:161], v[2:17]
	s_add_i32 s11, s42, 16
	s_waitcnt vmcnt(6) lgkmcnt(0)
	s_barrier
	v_add_u32_e32 v158, s11, v219
	v_add_u32_e32 v170, s11, v218
	v_add_u32_e32 v158, v158, v0
	v_add_u32_e32 v170, v170, v0
	ds_read_b128 v[154:157], v158
	ds_read_b128 v[182:185], v170 offset:8192
	ds_read_b128 v[178:181], v170 offset:10240
	ds_read_b128 v[158:161], v158 offset:2048
	ds_read_b128 v[174:177], v170 offset:12288
	ds_read_b128 v[170:173], v170 offset:14336
	v_mfma_f32_32x32x16_bf16 v[114:129], v[162:165], v[138:141], v[114:129]
	v_mfma_f32_32x32x16_bf16 v[98:113], v[166:169], v[138:141], v[98:113]
	v_mfma_f32_32x32x16_bf16 v[66:81], v[162:165], v[142:145], v[66:81]
	v_mfma_f32_32x32x16_bf16 v[34:49], v[166:169], v[142:145], v[34:49]
	v_mfma_f32_32x32x16_bf16 v[82:97], v[146:149], v[138:141], v[82:97]
	v_mfma_f32_32x32x16_bf16 v[50:65], v[150:153], v[138:141], v[50:65]
	v_mfma_f32_32x32x16_bf16 v[18:33], v[146:149], v[142:145], v[18:33]
	v_mfma_f32_32x32x16_bf16 v[2:17], v[150:153], v[142:145], v[2:17]
	s_add_i32 s40, s40, 2
	s_cmp_lg_u32 s40, 30
	s_cbranch_scc1 .LBB0_21
; #define LAS __attribute__((address_space(3)))
; DI unsigned pk2(float a, float b) { f32x2 v = {a, b}; bf2_t r = __builtin_convertvector(v, bf2_t); return __builtin_bit_cast(unsigned, r); }
; DI f32x16 mfma32(bf16x8 a, bf16x8 b, f32x16 c) { return __builtin_amdgcn_mfma_f32_32x32x16_bf16(a, b, c, 0, 0, 0); }
;     ...
;   for (int kt = 0; kt < nk; ++kt) {
;     const int kn = (kt + 2 < nk) ? (kt + 2) : (nk - 1);
;     const LAS char* cur = lds + s0;
;     bf16x8 af[2][2], bfr[2][4];
; #pragma unroll
;     for (int kk = 0; kk < 2; ++kk) {
;       const int xo = kk ? x1 : x0;
;       af[kk][0] = *(const LAS bf16x8*)(cur + a_rd + xo);
;       bfr[kk][0] = *(const LAS bf16x8*)(cur + b_rd + xo);
;       bfr[kk][1] = *(const LAS bf16x8*)(cur + b_rd + 2048 + xo);
;       af[kk][1] = *(const LAS bf16x8*)(cur + a_rd + 2048 + xo);
;       bfr[kk][2] = *(const LAS bf16x8*)(cur + b_rd + 4096 + xo);
;       bfr[kk][3] = *(const LAS bf16x8*)(cur + b_rd + 6144 + xo);
;     }
;     DMA_STEP_(kn, s2);
; #pragma unroll
;     for (int kk = 0; kk < 2; ++kk) {
;       acc[0][0] = mfma32(bfr[kk][0], af[kk][0], acc[0][0]); acc[0][1] = mfma32(bfr[kk][1], af[kk][0], acc[0][1]);
;       acc[1][0] = mfma32(bfr[kk][0], af[kk][1], acc[1][0]); acc[1][1] = mfma32(bfr[kk][1], af[kk][1], acc[1][1]);
;       acc[0][2] = mfma32(bfr[kk][2], af[kk][0], acc[0][2]); acc[0][3] = mfma32(bfr[kk][3], af[kk][0], acc[0][3]);
;       acc[1][2] = mfma32(bfr[kk][2], af[kk][1], acc[1][2]); acc[1][3] = mfma32(bfr[kk][3], af[kk][1], acc[1][3]);
;     }
;     __builtin_amdgcn_sched_group_barrier(0x100, 12, 0);
;     __builtin_amdgcn_sched_group_barrier(0x010, 6, 0);
;     __builtin_amdgcn_sched_group_barrier(0x008, 16, 0);
;     asm volatile("s_waitcnt vmcnt(6) lgkmcnt(0)" ::: "memory");
;     __builtin_amdgcn_s_barrier();
;     asm volatile("" ::: "memory");
;     s0 = (s0 == 2 * STG) ? 0 : s0 + STG;
;     s2 = (s2 == 2 * STG) ? 0 : s2 + STG;
;   }
;     ...
;   {
;     const int h = lane >> 5, cl = lane & 31;
; #pragma unroll
;     for (int i = 0; i < 2; ++i)
; #pragma unroll
;       for (int j = 0; j < 4; ++j)
; #pragma unroll
;         for (int g = 0; g < 4; ++g) {
;           u32x2 w; w.x = pk2(acc[i][j][4 * g], acc[i][j][4 * g + 1]); w.y = pk2(acc[i][j][4 * g + 2], acc[i][j][4 * g + 3]);
;           *(u32x2*)(smem + (wr * 64 + i * 32 + cl) * 528 + (wc * 128 + j * 32 + 8 * g + 4 * h) * 2) = w;
;         }
;   }
	s_add_i32 s11, s42, 16
	v_add_u32_e32 v142, s11, v219
	v_add_u32_e32 v150, s11, v218
	v_add_u32_e32 v142, v142, v220
	v_add_u32_e32 v150, v150, v220
	ds_read_b128 v[138:141], v142
	ds_read_b128 v[162:165], v150 offset:8192
	ds_read_b128 v[166:169], v150 offset:10240
	ds_read_b128 v[142:145], v142 offset:2048
	ds_read_b128 v[146:149], v150 offset:12288
	ds_read_b128 v[150:153], v150 offset:14336
	s_waitcnt lgkmcnt(6)
	v_mfma_f32_32x32x16_bf16 v[114:129], v[182:185], v[154:157], v[114:129]
	v_mfma_f32_32x32x16_bf16 v[98:113], v[178:181], v[154:157], v[98:113]
	v_mfma_f32_32x32x16_bf16 v[66:81], v[182:185], v[158:161], v[66:81]
	v_mfma_f32_32x32x16_bf16 v[34:49], v[178:181], v[158:161], v[34:49]
	v_mfma_f32_32x32x16_bf16 v[82:97], v[174:177], v[154:157], v[82:97]
	v_mfma_f32_32x32x16_bf16 v[50:65], v[170:173], v[154:157], v[50:65]
	v_mfma_f32_32x32x16_bf16 v[18:33], v[174:177], v[158:161], v[18:33]
	s_add_i32 s10, s42, 0x6000
	s_cmpk_lg_u32 s42, 0xc000
	s_cselect_b32 s42, s10, 0
	v_mfma_f32_32x32x16_bf16 v[2:17], v[170:173], v[158:161], v[2:17]
	s_add_i32 s11, s42, 16
	s_waitcnt vmcnt(0) lgkmcnt(0)
	s_barrier
	v_add_u32_e32 v158, s11, v219
	v_add_u32_e32 v170, s11, v218
	v_add_u32_e32 v158, v158, v0
	v_add_u32_e32 v170, v170, v0
	ds_read_b128 v[154:157], v158
	ds_read_b128 v[182:185], v170 offset:8192
	ds_read_b128 v[178:181], v170 offset:10240
	ds_read_b128 v[158:161], v158 offset:2048
	ds_read_b128 v[174:177], v170 offset:12288
	ds_read_b128 v[170:173], v170 offset:14336
	v_mfma_f32_32x32x16_bf16 v[114:129], v[162:165], v[138:141], v[114:129]
	v_mfma_f32_32x32x16_bf16 v[98:113], v[166:169], v[138:141], v[98:113]
	v_mfma_f32_32x32x16_bf16 v[66:81], v[162:165], v[142:145], v[66:81]
	v_mfma_f32_32x32x16_bf16 v[34:49], v[166:169], v[142:145], v[34:49]
	v_mfma_f32_32x32x16_bf16 v[82:97], v[146:149], v[138:141], v[82:97]
	v_mfma_f32_32x32x16_bf16 v[50:65], v[150:153], v[138:141], v[50:65]
	v_mfma_f32_32x32x16_bf16 v[18:33], v[146:149], v[142:145], v[18:33]
	v_mfma_f32_32x32x16_bf16 v[2:17], v[150:153], v[142:145], v[2:17]
	s_add_i32 s11, s42, 16
	v_add_u32_e32 v142, s11, v219
	v_add_u32_e32 v150, s11, v218
	v_add_u32_e32 v142, v142, v220
	v_add_u32_e32 v150, v150, v220
	ds_read_b128 v[138:141], v142
	ds_read_b128 v[162:165], v150 offset:8192
	ds_read_b128 v[166:169], v150 offset:10240
	ds_read_b128 v[142:145], v142 offset:2048
	ds_read_b128 v[146:149], v150 offset:12288
	ds_read_b128 v[150:153], v150 offset:14336
	s_waitcnt lgkmcnt(6)
	v_mfma_f32_32x32x16_bf16 v[114:129], v[182:185], v[154:157], v[114:129]
	v_mfma_f32_32x32x16_bf16 v[98:113], v[178:181], v[154:157], v[98:113]
	v_mfma_f32_32x32x16_bf16 v[66:81], v[182:185], v[158:161], v[66:81]
	v_mfma_f32_32x32x16_bf16 v[34:49], v[178:181], v[158:161], v[34:49]
	v_mfma_f32_32x32x16_bf16 v[82:97], v[174:177], v[154:157], v[82:97]
	v_mfma_f32_32x32x16_bf16 v[50:65], v[170:173], v[154:157], v[50:65]
	v_mfma_f32_32x32x16_bf16 v[18:33], v[174:177], v[158:161], v[18:33]
	v_mfma_f32_32x32x16_bf16 v[2:17], v[170:173], v[158:161], v[2:17]
	s_waitcnt lgkmcnt(0)
	v_mfma_f32_32x32x16_bf16 v[114:129], v[162:165], v[138:141], v[114:129]
	v_mfma_f32_32x32x16_bf16 v[98:113], v[166:169], v[138:141], v[98:113]
	v_mfma_f32_32x32x16_bf16 v[66:81], v[162:165], v[142:145], v[66:81]
	v_mfma_f32_32x32x16_bf16 v[34:49], v[166:169], v[142:145], v[34:49]
	v_mfma_f32_32x32x16_bf16 v[82:97], v[146:149], v[138:141], v[82:97]
	v_mfma_f32_32x32x16_bf16 v[50:65], v[150:153], v[138:141], v[50:65]
	v_mfma_f32_32x32x16_bf16 v[18:33], v[146:149], v[142:145], v[18:33]
	v_mfma_f32_32x32x16_bf16 v[2:17], v[150:153], v[142:145], v[2:17]
	s_waitcnt lgkmcnt(0)
	s_setprio 0
	v_mul_lo_u32 v0, v197, s55
	v_add_u32_e32 v0, 16, v0
	s_nop 1
	v_cvt_pk_bf16_f32 v114, v114, v115
	v_cvt_pk_bf16_f32 v115, v116, v117
	v_lshlrev_b32_e32 v116, 3, v196
	s_lshl_b32 s10, s28, 1
	v_add3_u32 v0, v0, v116, s10
	v_cvt_pk_bf16_f32 v116, v118, v119
	v_cvt_pk_bf16_f32 v117, v120, v121
	v_cvt_pk_bf16_f32 v98, v98, v99
	v_cvt_pk_bf16_f32 v99, v100, v101
	v_cvt_pk_bf16_f32 v100, v102, v103
	v_cvt_pk_bf16_f32 v101, v104, v105
	v_cvt_pk_bf16_f32 v82, v82, v83
	v_cvt_pk_bf16_f32 v83, v84, v85
	v_cvt_pk_bf16_f32 v84, v86, v87
	v_cvt_pk_bf16_f32 v85, v88, v89
	v_cvt_pk_bf16_f32 v50, v50, v51
	v_cvt_pk_bf16_f32 v51, v52, v53
	v_cvt_pk_bf16_f32 v52, v54, v55
	v_cvt_pk_bf16_f32 v53, v56, v57
	s_waitcnt vmcnt(0)
	s_barrier
; DI unsigned pk2(float a, float b) { f32x2 v = {a, b}; bf2_t r = __builtin_convertvector(v, bf2_t); return __builtin_bit_cast(unsigned, r); }
;     ...
;   {
;     const int h = lane >> 5, cl = lane & 31;
; #pragma unroll
;     for (int i = 0; i < 2; ++i)
; #pragma unroll
;       for (int j = 0; j < 4; ++j)
; #pragma unroll
;         for (int g = 0; g < 4; ++g) {
;           u32x2 w; w.x = pk2(acc[i][j][4 * g], acc[i][j][4 * g + 1]); w.y = pk2(acc[i][j][4 * g + 2], acc[i][j][4 * g + 3]);
;           *(u32x2*)(smem + (wr * 64 + i * 32 + cl) * 528 + (wc * 128 + j * 32 + 8 * g + 4 * h) * 2) = w;
;         }
;   }
	ds_write2_b64 v0, v[114:115], v[116:117] offset1:2
	v_cvt_pk_bf16_f32 v114, v122, v123
	v_cvt_pk_bf16_f32 v115, v124, v125
	v_cvt_pk_bf16_f32 v116, v126, v127
	v_cvt_pk_bf16_f32 v117, v128, v129
	ds_write2_b64 v0, v[98:99], v[100:101] offset0:8 offset1:10
	v_cvt_pk_bf16_f32 v98, v106, v107
	v_cvt_pk_bf16_f32 v99, v108, v109
	v_cvt_pk_bf16_f32 v100, v110, v111
	v_cvt_pk_bf16_f32 v101, v112, v113
	ds_write2_b64 v0, v[82:83], v[84:85] offset0:16 offset1:18
	v_cvt_pk_bf16_f32 v82, v90, v91
	v_cvt_pk_bf16_f32 v83, v92, v93
	v_cvt_pk_bf16_f32 v84, v94, v95
	v_cvt_pk_bf16_f32 v85, v96, v97
	ds_write2_b64 v0, v[50:51], v[52:53] offset0:24 offset1:26
	v_cvt_pk_bf16_f32 v50, v58, v59
	v_cvt_pk_bf16_f32 v51, v60, v61
	v_cvt_pk_bf16_f32 v52, v62, v63
	v_cvt_pk_bf16_f32 v53, v64, v65
	ds_write2_b64 v0, v[114:115], v[116:117] offset0:4 offset1:6
	ds_write2_b64 v0, v[98:99], v[100:101] offset0:12 offset1:14
	ds_write2_b64 v0, v[82:83], v[84:85] offset0:20 offset1:22
	ds_write2_b64 v0, v[50:51], v[52:53] offset0:28 offset1:30
	v_cvt_pk_bf16_f32 v50, v66, v67
	v_cvt_pk_bf16_f32 v51, v68, v69
	v_cvt_pk_bf16_f32 v52, v70, v71
	v_cvt_pk_bf16_f32 v53, v72, v73
	v_add_u32_e32 v0, 0x4000, v0
	v_cvt_pk_bf16_f32 v34, v34, v35
	v_cvt_pk_bf16_f32 v35, v36, v37
	v_cvt_pk_bf16_f32 v36, v38, v39
	v_cvt_pk_bf16_f32 v37, v40, v41
	v_cvt_pk_bf16_f32 v18, v18, v19
	v_cvt_pk_bf16_f32 v19, v20, v21
	v_cvt_pk_bf16_f32 v20, v22, v23
	v_cvt_pk_bf16_f32 v21, v24, v25
	v_cvt_pk_bf16_f32 v2, v2, v3
	v_cvt_pk_bf16_f32 v3, v4, v5
	v_cvt_pk_bf16_f32 v4, v6, v7
	v_cvt_pk_bf16_f32 v5, v8, v9
	ds_write2_b64 v0, v[50:51], v[52:53] offset0:64 offset1:66
	v_cvt_pk_bf16_f32 v50, v74, v75
	v_cvt_pk_bf16_f32 v51, v76, v77
	v_cvt_pk_bf16_f32 v52, v78, v79
	v_cvt_pk_bf16_f32 v53, v80, v81
	ds_write2_b64 v0, v[34:35], v[36:37] offset0:72 offset1:74
	v_cvt_pk_bf16_f32 v34, v42, v43
	v_cvt_pk_bf16_f32 v35, v44, v45
	v_cvt_pk_bf16_f32 v36, v46, v47
	v_cvt_pk_bf16_f32 v37, v48, v49
	ds_write2_b64 v0, v[18:19], v[20:21] offset0:80 offset1:82
	v_cvt_pk_bf16_f32 v18, v26, v27
	v_cvt_pk_bf16_f32 v19, v28, v29
	v_cvt_pk_bf16_f32 v20, v30, v31
	v_cvt_pk_bf16_f32 v21, v32, v33
	ds_write2_b64 v0, v[2:3], v[4:5] offset0:88 offset1:90
	v_cvt_pk_bf16_f32 v2, v10, v11
	v_cvt_pk_bf16_f32 v3, v12, v13
	v_cvt_pk_bf16_f32 v4, v14, v15
	v_cvt_pk_bf16_f32 v5, v16, v17
	s_lshl_b64 s[14:15], s[14:15], 1
	ds_write2_b64 v0, v[50:51], v[52:53] offset0:68 offset1:70
	ds_write2_b64 v0, v[34:35], v[36:37] offset0:76 offset1:78
	ds_write2_b64 v0, v[18:19], v[20:21] offset0:84 offset1:86
	ds_write2_b64 v0, v[2:3], v[4:5] offset0:92 offset1:94
	s_waitcnt vmcnt(0) lgkmcnt(0)
	s_barrier
; #define GAS __attribute__((address_space(1)))
;     ...
;   int tid2 = tid; asm volatile("" : "+v"(tid2));
;   if (EPI == 0) {
; #pragma unroll
;     for (int i = 0; i < 16; ++i) {
;       const int id = tid2 + 256 * i, r = id >> 5, c8 = (id & 31) * 8;
;       const u32x4 v = *(const u32x4*)(smem + r * 528 + c8 * 2);
;       *(GAS u32x4*)(ea.out + (size_t)(m0 + r) * ea.ldo + n0 + c8) = v;
;     }
	s_add_u32 s14, s19, s14
	v_lshlrev_b32_e32 v0, 4, v189
	v_and_b32_e32 v0, 0x1f0, v0
	s_addc_u32 s15, s20, s15
	v_add_u32_e32 v10, 16, v0
	v_lshl_add_u64 v[12:13], s[14:15], 0, v[0:1]
	v_ashrrev_i32_e32 v0, 5, v189
	v_mad_u64_u32 v[2:3], s[14:15], v0, s55, v[10:11]
	ds_read_b128 v[2:5], v2
	v_add_u32_e32 v6, s12, v0
	v_ashrrev_i32_e32 v7, 31, v6
	v_add_u32_e32 v0, 0x100, v189
	v_lshlrev_b64 v[6:7], 11, v[6:7]
	v_ashrrev_i32_e32 v0, 5, v0
	v_lshl_add_u64 v[14:15], v[12:13], 0, v[6:7]
	v_mad_u64_u32 v[6:7], s[14:15], v0, s55, v[10:11]
	ds_read_b128 v[6:9], v6
	s_waitcnt lgkmcnt(1)
	global_store_dwordx4 v[14:15], v[2:5], off nt
	v_readlane_b32 s10, v252, 12
	s_add_i32 s23, s23, s10
	v_add_u32_e32 v2, s12, v0
	v_ashrrev_i32_e32 v3, 31, v2
	v_lshlrev_b64 v[2:3], 11, v[2:3]
	v_add_u32_e32 v0, 0x200, v189
	v_lshl_add_u64 v[2:3], v[12:13], 0, v[2:3]
	v_ashrrev_i32_e32 v0, 5, v0
	s_waitcnt lgkmcnt(0)
	global_store_dwordx4 v[2:3], v[6:9], off nt
	v_mad_u64_u32 v[2:3], s[14:15], v0, s55, v[10:11]
	ds_read_b128 v[2:5], v2
	v_add_u32_e32 v6, s12, v0
	v_ashrrev_i32_e32 v7, 31, v6
	v_add_u32_e32 v0, 0x300, v189
	v_lshlrev_b64 v[6:7], 11, v[6:7]
	v_ashrrev_i32_e32 v0, 5, v0
	v_lshl_add_u64 v[14:15], v[12:13], 0, v[6:7]
	v_mad_u64_u32 v[6:7], s[14:15], v0, s55, v[10:11]
	ds_read_b128 v[6:9], v6
	s_waitcnt lgkmcnt(1)
	global_store_dwordx4 v[14:15], v[2:5], off nt
	s_cmp_ge_i32 s23, s16
	s_nop 0
	v_add_u32_e32 v2, s12, v0
	v_ashrrev_i32_e32 v3, 31, v2
	v_lshlrev_b64 v[2:3], 11, v[2:3]
	v_add_u32_e32 v0, 0x400, v189
	v_lshl_add_u64 v[2:3], v[12:13], 0, v[2:3]
	v_ashrrev_i32_e32 v0, 5, v0
	s_waitcnt lgkmcnt(0)
	global_store_dwordx4 v[2:3], v[6:9], off nt
	v_mad_u64_u32 v[2:3], s[14:15], v0, s55, v[10:11]
	ds_read_b128 v[2:5], v2
	v_add_u32_e32 v6, s12, v0
	v_ashrrev_i32_e32 v7, 31, v6
	v_add_u32_e32 v0, 0x500, v189
	v_lshlrev_b64 v[6:7], 11, v[6:7]
	v_ashrrev_i32_e32 v0, 5, v0
	v_lshl_add_u64 v[14:15], v[12:13], 0, v[6:7]
	v_mad_u64_u32 v[6:7], s[14:15], v0, s55, v[10:11]
	ds_read_b128 v[6:9], v6
	s_waitcnt lgkmcnt(1)
	global_store_dwordx4 v[14:15], v[2:5], off nt
	s_nop 1
	v_add_u32_e32 v2, s12, v0
	v_ashrrev_i32_e32 v3, 31, v2
	v_lshlrev_b64 v[2:3], 11, v[2:3]
	v_add_u32_e32 v0, 0x600, v189
	v_lshl_add_u64 v[2:3], v[12:13], 0, v[2:3]
	v_ashrrev_i32_e32 v0, 5, v0
	s_waitcnt lgkmcnt(0)
	global_store_dwordx4 v[2:3], v[6:9], off nt
	v_mad_u64_u32 v[2:3], s[14:15], v0, s55, v[10:11]
	ds_read_b128 v[2:5], v2
	v_add_u32_e32 v6, s12, v0
	v_ashrrev_i32_e32 v7, 31, v6
	v_add_u32_e32 v0, 0x700, v189
	v_lshlrev_b64 v[6:7], 11, v[6:7]
	v_ashrrev_i32_e32 v0, 5, v0
	v_lshl_add_u64 v[14:15], v[12:13], 0, v[6:7]
	v_mad_u64_u32 v[6:7], s[14:15], v0, s55, v[10:11]
	ds_read_b128 v[6:9], v6
	s_waitcnt lgkmcnt(1)
	global_store_dwordx4 v[14:15], v[2:5], off nt
	s_nop 1
	v_add_u32_e32 v2, s12, v0
	v_ashrrev_i32_e32 v3, 31, v2
	v_lshlrev_b64 v[2:3], 11, v[2:3]
	v_add_u32_e32 v0, 0x800, v189
	v_lshl_add_u64 v[2:3], v[12:13], 0, v[2:3]
	v_ashrrev_i32_e32 v0, 5, v0
	s_waitcnt lgkmcnt(0)
	global_store_dwordx4 v[2:3], v[6:9], off nt
	v_mad_u64_u32 v[2:3], s[14:15], v0, s55, v[10:11]
	ds_read_b128 v[2:5], v2
	v_add_u32_e32 v6, s12, v0
	v_ashrrev_i32_e32 v7, 31, v6
	v_add_u32_e32 v0, 0x900, v189
	v_lshlrev_b64 v[6:7], 11, v[6:7]
	v_ashrrev_i32_e32 v0, 5, v0
	v_lshl_add_u64 v[14:15], v[12:13], 0, v[6:7]
	v_mad_u64_u32 v[6:7], s[14:15], v0, s55, v[10:11]
	ds_read_b128 v[6:9], v6
	s_waitcnt lgkmcnt(1)
	global_store_dwordx4 v[14:15], v[2:5], off nt
	s_nop 1
	v_add_u32_e32 v2, s12, v0
	v_ashrrev_i32_e32 v3, 31, v2
	v_lshlrev_b64 v[2:3], 11, v[2:3]
	v_add_u32_e32 v0, 0xa00, v189
	v_lshl_add_u64 v[2:3], v[12:13], 0, v[2:3]
	v_ashrrev_i32_e32 v0, 5, v0
	s_waitcnt lgkmcnt(0)
	global_store_dwordx4 v[2:3], v[6:9], off nt
	v_mad_u64_u32 v[2:3], s[14:15], v0, s55, v[10:11]
	ds_read_b128 v[2:5], v2
	v_add_u32_e32 v6, s12, v0
	v_ashrrev_i32_e32 v7, 31, v6
	v_add_u32_e32 v0, 0xb00, v189
	v_lshlrev_b64 v[6:7], 11, v[6:7]
	v_ashrrev_i32_e32 v0, 5, v0
	v_lshl_add_u64 v[14:15], v[12:13], 0, v[6:7]
	v_mad_u64_u32 v[6:7], s[14:15], v0, s55, v[10:11]
	ds_read_b128 v[6:9], v6
	s_waitcnt lgkmcnt(1)
	global_store_dwordx4 v[14:15], v[2:5], off nt
	s_nop 1
	v_add_u32_e32 v2, s12, v0
	v_ashrrev_i32_e32 v3, 31, v2
	v_lshlrev_b64 v[2:3], 11, v[2:3]
	v_add_u32_e32 v0, 0xc00, v189
	v_lshl_add_u64 v[2:3], v[12:13], 0, v[2:3]
	v_ashrrev_i32_e32 v0, 5, v0
	s_waitcnt lgkmcnt(0)
	global_store_dwordx4 v[2:3], v[6:9], off nt
	v_mad_u64_u32 v[2:3], s[14:15], v0, s55, v[10:11]
	ds_read_b128 v[2:5], v2
	v_add_u32_e32 v6, s12, v0
	v_ashrrev_i32_e32 v7, 31, v6
	v_add_u32_e32 v0, 0xd00, v189
	v_lshlrev_b64 v[6:7], 11, v[6:7]
	v_ashrrev_i32_e32 v0, 5, v0
	v_lshl_add_u64 v[14:15], v[12:13], 0, v[6:7]
	v_mad_u64_u32 v[6:7], s[14:15], v0, s55, v[10:11]
	ds_read_b128 v[6:9], v6
	s_waitcnt lgkmcnt(1)
	global_store_dwordx4 v[14:15], v[2:5], off nt
	s_nop 1
	v_add_u32_e32 v2, s12, v0
	v_ashrrev_i32_e32 v3, 31, v2
	v_lshlrev_b64 v[2:3], 11, v[2:3]
	v_add_u32_e32 v0, 0xe00, v189
	v_lshl_add_u64 v[2:3], v[12:13], 0, v[2:3]
	v_ashrrev_i32_e32 v0, 5, v0
	s_waitcnt lgkmcnt(0)
	global_store_dwordx4 v[2:3], v[6:9], off nt
	v_mad_u64_u32 v[2:3], s[14:15], v0, s55, v[10:11]
	ds_read_b128 v[2:5], v2
	v_add_u32_e32 v6, s12, v0
	v_ashrrev_i32_e32 v7, 31, v6
	v_add_u32_e32 v0, 0xf00, v189
	v_lshlrev_b64 v[6:7], 11, v[6:7]
	v_ashrrev_i32_e32 v0, 5, v0
	v_lshl_add_u64 v[14:15], v[12:13], 0, v[6:7]
	v_mad_u64_u32 v[6:7], s[14:15], v0, s55, v[10:11]
	ds_read_b128 v[6:9], v6
	s_waitcnt lgkmcnt(1)
	global_store_dwordx4 v[14:15], v[2:5], off nt
	s_nop 1
	v_add_u32_e32 v2, s12, v0
	v_ashrrev_i32_e32 v3, 31, v2
	v_lshlrev_b64 v[2:3], 11, v[2:3]
	v_lshl_add_u64 v[2:3], v[12:13], 0, v[2:3]
	s_waitcnt lgkmcnt(0)
	global_store_dwordx4 v[2:3], v[6:9], off nt
	s_barrier
	s_cbranch_scc0 .LBB0_20

; #define LAS __attribute__((address_space(3)))
; DI f32x16 mfma32(bf16x8 a, bf16x8 b, f32x16 c) { return __builtin_amdgcn_mfma_f32_32x32x16_bf16(a, b, c, 0, 0, 0); }
;     ...
;   for (int kt = 0; kt < nk; ++kt) {
;     const int kn = (kt + 2 < nk) ? (kt + 2) : (nk - 1);
;     const LAS char* cur = lds + s0;
;     bf16x8 af[2][2], bfr[2][4];
; #pragma unroll
;     for (int kk = 0; kk < 2; ++kk) {
;       const int xo = kk ? x1 : x0;
;       af[kk][0] = *(const LAS bf16x8*)(cur + a_rd + xo);
;       bfr[kk][0] = *(const LAS bf16x8*)(cur + b_rd + xo);
;       bfr[kk][1] = *(const LAS bf16x8*)(cur + b_rd + 2048 + xo);
;       af[kk][1] = *(const LAS bf16x8*)(cur + a_rd + 2048 + xo);
;       bfr[kk][2] = *(const LAS bf16x8*)(cur + b_rd + 4096 + xo);
;       bfr[kk][3] = *(const LAS bf16x8*)(cur + b_rd + 6144 + xo);
;     }
;     DMA_STEP_(kn, s2);
; #pragma unroll
;     for (int kk = 0; kk < 2; ++kk) {
;       acc[0][0] = mfma32(bfr[kk][0], af[kk][0], acc[0][0]); acc[0][1] = mfma32(bfr[kk][1], af[kk][0], acc[0][1]);
;       acc[1][0] = mfma32(bfr[kk][0], af[kk][1], acc[1][0]); acc[1][1] = mfma32(bfr[kk][1], af[kk][1], acc[1][1]);
;       acc[0][2] = mfma32(bfr[kk][2], af[kk][0], acc[0][2]); acc[0][3] = mfma32(bfr[kk][3], af[kk][0], acc[0][3]);
;       acc[1][2] = mfma32(bfr[kk][2], af[kk][1], acc[1][2]); acc[1][3] = mfma32(bfr[kk][3], af[kk][1], acc[1][3]);
;     }
;     __builtin_amdgcn_sched_group_barrier(0x100, 12, 0);
;     __builtin_amdgcn_sched_group_barrier(0x010, 6, 0);
;     __builtin_amdgcn_sched_group_barrier(0x008, 16, 0);
;     asm volatile("s_waitcnt vmcnt(6) lgkmcnt(0)" ::: "memory");
;     __builtin_amdgcn_s_barrier();
;     asm volatile("" ::: "memory");
;     s0 = (s0 == 2 * STG) ? 0 : s0 + STG;
;     s2 = (s2 == 2 * STG) ? 0 : s2 + STG;
;   }
.LBB0_184:
	s_add_i32 s11, s29, 16
	s_mov_b32 s10, s23
	v_add_u32_e32 v142, s11, v219
	v_add_u32_e32 v150, s11, v218
	s_min_u32 s10, s10, 29
	v_add_u32_e32 v142, v142, v220
	v_add_u32_e32 v150, v150, v220
	s_lshl_b32 s70, s10, 6
	ds_read_b128 v[138:141], v142
	ds_read_b128 v[162:165], v150 offset:8192
	ds_read_b128 v[166:169], v150 offset:10240
	ds_read_b128 v[142:145], v142 offset:2048
	ds_read_b128 v[146:149], v150 offset:12288
	ds_read_b128 v[150:153], v150 offset:14336
	s_mul_i32 vcc_lo, s70, 0x12000
	s_add_i32 s10, s13, s28
	v_lshl_add_u64 v[222:223], v[192:193], 0, vcc
	s_mov_b32 m0, s10
	s_mul_i32 s100, s70, 0x900
	v_lshl_add_u64 v[224:225], v[194:195], 0, s[100:101]
	s_add_i32 s10, s22, s28
	s_waitcnt lgkmcnt(6)
	v_mfma_f32_32x32x16_bf16 v[114:129], v[182:185], v[154:157], v[114:129]
	global_load_lds_dwordx4 v[222:223], off
	v_mfma_f32_32x32x16_bf16 v[98:113], v[178:181], v[154:157], v[98:113]
	global_load_lds_dwordx4 v[222:223], off offset:1024
	s_add_i32 m0, s10, 0x2000
	v_mfma_f32_32x32x16_bf16 v[66:81], v[182:185], v[158:161], v[66:81]
	global_load_lds_dwordx4 v[224:225], off
	v_mfma_f32_32x32x16_bf16 v[34:49], v[178:181], v[158:161], v[34:49]
	global_load_lds_dwordx4 v[224:225], off offset:1024
	v_mfma_f32_32x32x16_bf16 v[82:97], v[174:177], v[154:157], v[82:97]
	global_load_lds_dwordx4 v[224:225], off offset:2048
	v_mfma_f32_32x32x16_bf16 v[50:65], v[170:173], v[154:157], v[50:65]
	global_load_lds_dwordx4 v[224:225], off offset:3072
	v_mfma_f32_32x32x16_bf16 v[18:33], v[174:177], v[158:161], v[18:33]
	s_add_i32 s10, s29, 0x6000
	s_cmpk_lg_u32 s29, 0xc000
	s_cselect_b32 s29, s10, 0
	s_add_i32 s10, s28, 0x6000
	s_cmpk_lg_u32 s28, 0xc000
	s_cselect_b32 s28, s10, 0
	v_mfma_f32_32x32x16_bf16 v[2:17], v[170:173], v[158:161], v[2:17]
	s_add_i32 s11, s29, 16
	s_waitcnt vmcnt(6) lgkmcnt(0)
	s_barrier
	v_add_u32_e32 v158, s11, v219
	v_add_u32_e32 v170, s11, v218
	v_add_u32_e32 v158, v158, v0
	v_add_u32_e32 v170, v170, v0
	ds_read_b128 v[154:157], v158
	ds_read_b128 v[182:185], v170 offset:8192
	ds_read_b128 v[178:181], v170 offset:10240
	ds_read_b128 v[158:161], v158 offset:2048
	ds_read_b128 v[174:177], v170 offset:12288
	ds_read_b128 v[170:173], v170 offset:14336
	v_mfma_f32_32x32x16_bf16 v[114:129], v[162:165], v[138:141], v[114:129]
	v_mfma_f32_32x32x16_bf16 v[98:113], v[166:169], v[138:141], v[98:113]
	v_mfma_f32_32x32x16_bf16 v[66:81], v[162:165], v[142:145], v[66:81]
	v_mfma_f32_32x32x16_bf16 v[34:49], v[166:169], v[142:145], v[34:49]
	v_mfma_f32_32x32x16_bf16 v[82:97], v[146:149], v[138:141], v[82:97]
	v_mfma_f32_32x32x16_bf16 v[50:65], v[150:153], v[138:141], v[50:65]
	v_mfma_f32_32x32x16_bf16 v[18:33], v[146:149], v[142:145], v[18:33]
	v_mfma_f32_32x32x16_bf16 v[2:17], v[150:153], v[142:145], v[2:17]
	s_add_i32 s11, s29, 16
	s_add_i32 s10, s23, 1
	v_add_u32_e32 v142, s11, v219
	v_add_u32_e32 v150, s11, v218
	s_min_u32 s10, s10, 29
	v_add_u32_e32 v142, v142, v220
	v_add_u32_e32 v150, v150, v220
	s_lshl_b32 s70, s10, 6
	ds_read_b128 v[138:141], v142
	ds_read_b128 v[162:165], v150 offset:8192
	ds_read_b128 v[166:169], v150 offset:10240
	ds_read_b128 v[142:145], v142 offset:2048
	ds_read_b128 v[146:149], v150 offset:12288
	ds_read_b128 v[150:153], v150 offset:14336
	s_mul_i32 vcc_lo, s70, 0x12000
	s_add_i32 s10, s13, s28
	v_lshl_add_u64 v[222:223], v[192:193], 0, vcc
	s_mov_b32 m0, s10
	s_mul_i32 s100, s70, 0x900
	v_lshl_add_u64 v[224:225], v[194:195], 0, s[100:101]
	s_add_i32 s10, s22, s28
	s_waitcnt lgkmcnt(6)
	v_mfma_f32_32x32x16_bf16 v[114:129], v[182:185], v[154:157], v[114:129]
	global_load_lds_dwordx4 v[222:223], off
	v_mfma_f32_32x32x16_bf16 v[98:113], v[178:181], v[154:157], v[98:113]
	global_load_lds_dwordx4 v[222:223], off offset:1024
	s_add_i32 m0, s10, 0x2000
	v_mfma_f32_32x32x16_bf16 v[66:81], v[182:185], v[158:161], v[66:81]
	global_load_lds_dwordx4 v[224:225], off
	v_mfma_f32_32x32x16_bf16 v[34:49], v[178:181], v[158:161], v[34:49]
	global_load_lds_dwordx4 v[224:225], off offset:1024
	v_mfma_f32_32x32x16_bf16 v[82:97], v[174:177], v[154:157], v[82:97]
	global_load_lds_dwordx4 v[224:225], off offset:2048
	v_mfma_f32_32x32x16_bf16 v[50:65], v[170:173], v[154:157], v[50:65]
	global_load_lds_dwordx4 v[224:225], off offset:3072
	v_mfma_f32_32x32x16_bf16 v[18:33], v[174:177], v[158:161], v[18:33]
	s_add_i32 s10, s29, 0x6000
	s_cmpk_lg_u32 s29, 0xc000
	s_cselect_b32 s29, s10, 0
	s_add_i32 s10, s28, 0x6000
	s_cmpk_lg_u32 s28, 0xc000
	s_cselect_b32 s28, s10, 0
	v_mfma_f32_32x32x16_bf16 v[2:17], v[170:173], v[158:161], v[2:17]
	s_add_i32 s11, s29, 16
	s_waitcnt vmcnt(6) lgkmcnt(0)
	s_barrier
	v_add_u32_e32 v158, s11, v219
	v_add_u32_e32 v170, s11, v218
	v_add_u32_e32 v158, v158, v0
	v_add_u32_e32 v170, v170, v0
	ds_read_b128 v[154:157], v158
	ds_read_b128 v[182:185], v170 offset:8192
	ds_read_b128 v[178:181], v170 offset:10240
	ds_read_b128 v[158:161], v158 offset:2048
	ds_read_b128 v[174:177], v170 offset:12288
	ds_read_b128 v[170:173], v170 offset:14336
	v_mfma_f32_32x32x16_bf16 v[114:129], v[162:165], v[138:141], v[114:129]
	v_mfma_f32_32x32x16_bf16 v[98:113], v[166:169], v[138:141], v[98:113]
	v_mfma_f32_32x32x16_bf16 v[66:81], v[162:165], v[142:145], v[66:81]
	v_mfma_f32_32x32x16_bf16 v[34:49], v[166:169], v[142:145], v[34:49]
	v_mfma_f32_32x32x16_bf16 v[82:97], v[146:149], v[138:141], v[82:97]
	v_mfma_f32_32x32x16_bf16 v[50:65], v[150:153], v[138:141], v[50:65]
	v_mfma_f32_32x32x16_bf16 v[18:33], v[146:149], v[142:145], v[18:33]
	v_mfma_f32_32x32x16_bf16 v[2:17], v[150:153], v[142:145], v[2:17]
	s_add_i32 s23, s23, 2
	s_cmp_lg_u32 s23, 30
	s_cbranch_scc1 .LBB0_184
; #define LAS __attribute__((address_space(3)))
; DI unsigned pk2(float a, float b) { f32x2 v = {a, b}; bf2_t r = __builtin_convertvector(v, bf2_t); return __builtin_bit_cast(unsigned, r); }
; DI f32x16 mfma32(bf16x8 a, bf16x8 b, f32x16 c) { return __builtin_amdgcn_mfma_f32_32x32x16_bf16(a, b, c, 0, 0, 0); }
;     ...
;   for (int kt = 0; kt < nk; ++kt) {
;     const int kn = (kt + 2 < nk) ? (kt + 2) : (nk - 1);
;     const LAS char* cur = lds + s0;
;     bf16x8 af[2][2], bfr[2][4];
; #pragma unroll
;     for (int kk = 0; kk < 2; ++kk) {
;       const int xo = kk ? x1 : x0;
;       af[kk][0] = *(const LAS bf16x8*)(cur + a_rd + xo);
;       bfr[kk][0] = *(const LAS bf16x8*)(cur + b_rd + xo);
;       bfr[kk][1] = *(const LAS bf16x8*)(cur + b_rd + 2048 + xo);
;       af[kk][1] = *(const LAS bf16x8*)(cur + a_rd + 2048 + xo);
;       bfr[kk][2] = *(const LAS bf16x8*)(cur + b_rd + 4096 + xo);
;       bfr[kk][3] = *(const LAS bf16x8*)(cur + b_rd + 6144 + xo);
;     }
;     DMA_STEP_(kn, s2);
; #pragma unroll
;     for (int kk = 0; kk < 2; ++kk) {
;       acc[0][0] = mfma32(bfr[kk][0], af[kk][0], acc[0][0]); acc[0][1] = mfma32(bfr[kk][1], af[kk][0], acc[0][1]);
;       acc[1][0] = mfma32(bfr[kk][0], af[kk][1], acc[1][0]); acc[1][1] = mfma32(bfr[kk][1], af[kk][1], acc[1][1]);
;       acc[0][2] = mfma32(bfr[kk][2], af[kk][0], acc[0][2]); acc[0][3] = mfma32(bfr[kk][3], af[kk][0], acc[0][3]);
;       acc[1][2] = mfma32(bfr[kk][2], af[kk][1], acc[1][2]); acc[1][3] = mfma32(bfr[kk][3], af[kk][1], acc[1][3]);
;     }
;     __builtin_amdgcn_sched_group_barrier(0x100, 12, 0);
;     __builtin_amdgcn_sched_group_barrier(0x010, 6, 0);
;     __builtin_amdgcn_sched_group_barrier(0x008, 16, 0);
;     asm volatile("s_waitcnt vmcnt(6) lgkmcnt(0)" ::: "memory");
;     __builtin_amdgcn_s_barrier();
;     asm volatile("" ::: "memory");
;     s0 = (s0 == 2 * STG) ? 0 : s0 + STG;
;     s2 = (s2 == 2 * STG) ? 0 : s2 + STG;
;   }
;     ...
;   {
;     const int h = lane >> 5, cl = lane & 31;
; #pragma unroll
;     for (int i = 0; i < 2; ++i)
; #pragma unroll
;       for (int j = 0; j < 4; ++j)
; #pragma unroll
;         for (int g = 0; g < 4; ++g) {
;           u32x2 w; w.x = pk2(acc[i][j][4 * g], acc[i][j][4 * g + 1]); w.y = pk2(acc[i][j][4 * g + 2], acc[i][j][4 * g + 3]);
;           *(u32x2*)(smem + (wr * 64 + i * 32 + cl) * 528 + (wc * 128 + j * 32 + 8 * g + 4 * h) * 2) = w;
;         }
;   }
	s_add_i32 s11, s29, 16
	v_add_u32_e32 v142, s11, v219
	v_add_u32_e32 v150, s11, v218
	v_add_u32_e32 v142, v142, v220
	v_add_u32_e32 v150, v150, v220
	ds_read_b128 v[138:141], v142
	ds_read_b128 v[162:165], v150 offset:8192
	ds_read_b128 v[166:169], v150 offset:10240
	ds_read_b128 v[142:145], v142 offset:2048
	ds_read_b128 v[146:149], v150 offset:12288
	ds_read_b128 v[150:153], v150 offset:14336
	s_waitcnt lgkmcnt(6)
	v_mfma_f32_32x32x16_bf16 v[114:129], v[182:185], v[154:157], v[114:129]
	v_mfma_f32_32x32x16_bf16 v[98:113], v[178:181], v[154:157], v[98:113]
	v_mfma_f32_32x32x16_bf16 v[66:81], v[182:185], v[158:161], v[66:81]
	v_mfma_f32_32x32x16_bf16 v[34:49], v[178:181], v[158:161], v[34:49]
	v_mfma_f32_32x32x16_bf16 v[82:97], v[174:177], v[154:157], v[82:97]
	v_mfma_f32_32x32x16_bf16 v[50:65], v[170:173], v[154:157], v[50:65]
	v_mfma_f32_32x32x16_bf16 v[18:33], v[174:177], v[158:161], v[18:33]
	s_add_i32 s10, s29, 0x6000
	s_cmpk_lg_u32 s29, 0xc000
	s_cselect_b32 s29, s10, 0
	v_mfma_f32_32x32x16_bf16 v[2:17], v[170:173], v[158:161], v[2:17]
	s_add_i32 s11, s29, 16
	s_waitcnt vmcnt(0) lgkmcnt(0)
	s_barrier
	v_add_u32_e32 v158, s11, v219
	v_add_u32_e32 v170, s11, v218
	v_add_u32_e32 v158, v158, v0
	v_add_u32_e32 v170, v170, v0
	ds_read_b128 v[154:157], v158
	ds_read_b128 v[182:185], v170 offset:8192
	ds_read_b128 v[178:181], v170 offset:10240
	ds_read_b128 v[158:161], v158 offset:2048
	ds_read_b128 v[174:177], v170 offset:12288
	ds_read_b128 v[170:173], v170 offset:14336
	v_mfma_f32_32x32x16_bf16 v[114:129], v[162:165], v[138:141], v[114:129]
	v_mfma_f32_32x32x16_bf16 v[98:113], v[166:169], v[138:141], v[98:113]
	v_mfma_f32_32x32x16_bf16 v[66:81], v[162:165], v[142:145], v[66:81]
	v_mfma_f32_32x32x16_bf16 v[34:49], v[166:169], v[142:145], v[34:49]
	v_mfma_f32_32x32x16_bf16 v[82:97], v[146:149], v[138:141], v[82:97]
	v_mfma_f32_32x32x16_bf16 v[50:65], v[150:153], v[138:141], v[50:65]
	v_mfma_f32_32x32x16_bf16 v[18:33], v[146:149], v[142:145], v[18:33]
	v_mfma_f32_32x32x16_bf16 v[2:17], v[150:153], v[142:145], v[2:17]
	s_add_i32 s11, s29, 16
	v_add_u32_e32 v142, s11, v219
	v_add_u32_e32 v150, s11, v218
	v_add_u32_e32 v142, v142, v220
	v_add_u32_e32 v150, v150, v220
	ds_read_b128 v[138:141], v142
	ds_read_b128 v[162:165], v150 offset:8192
	ds_read_b128 v[166:169], v150 offset:10240
	ds_read_b128 v[142:145], v142 offset:2048
	ds_read_b128 v[146:149], v150 offset:12288
	ds_read_b128 v[150:153], v150 offset:14336
	s_waitcnt lgkmcnt(6)
	v_mfma_f32_32x32x16_bf16 v[114:129], v[182:185], v[154:157], v[114:129]
	v_mfma_f32_32x32x16_bf16 v[98:113], v[178:181], v[154:157], v[98:113]
	v_mfma_f32_32x32x16_bf16 v[66:81], v[182:185], v[158:161], v[66:81]
	v_mfma_f32_32x32x16_bf16 v[34:49], v[178:181], v[158:161], v[34:49]
	v_mfma_f32_32x32x16_bf16 v[82:97], v[174:177], v[154:157], v[82:97]
	v_mfma_f32_32x32x16_bf16 v[50:65], v[170:173], v[154:157], v[50:65]
	v_mfma_f32_32x32x16_bf16 v[18:33], v[174:177], v[158:161], v[18:33]
	v_mfma_f32_32x32x16_bf16 v[2:17], v[170:173], v[158:161], v[2:17]
	s_waitcnt lgkmcnt(0)
	v_mfma_f32_32x32x16_bf16 v[114:129], v[162:165], v[138:141], v[114:129]
	v_mfma_f32_32x32x16_bf16 v[98:113], v[166:169], v[138:141], v[98:113]
	v_mfma_f32_32x32x16_bf16 v[66:81], v[162:165], v[142:145], v[66:81]
	v_mfma_f32_32x32x16_bf16 v[34:49], v[166:169], v[142:145], v[34:49]
	v_mfma_f32_32x32x16_bf16 v[82:97], v[146:149], v[138:141], v[82:97]
	v_mfma_f32_32x32x16_bf16 v[50:65], v[150:153], v[138:141], v[50:65]
	v_mfma_f32_32x32x16_bf16 v[18:33], v[146:149], v[142:145], v[18:33]
	v_mfma_f32_32x32x16_bf16 v[2:17], v[150:153], v[142:145], v[2:17]
	s_waitcnt lgkmcnt(0)
	s_setprio 0
	v_mul_lo_u32 v0, v197, s55
	v_add_u32_e32 v0, 16, v0
	s_nop 1
	v_cvt_pk_bf16_f32 v114, v114, v115
	v_cvt_pk_bf16_f32 v115, v116, v117
	v_lshlrev_b32_e32 v116, 3, v196
	s_lshl_b32 s10, s21, 1
	v_add3_u32 v0, v0, v116, s10
	v_cvt_pk_bf16_f32 v116, v118, v119
	v_cvt_pk_bf16_f32 v117, v120, v121
	v_cvt_pk_bf16_f32 v98, v98, v99
	v_cvt_pk_bf16_f32 v99, v100, v101
	v_cvt_pk_bf16_f32 v100, v102, v103
	v_cvt_pk_bf16_f32 v101, v104, v105
	v_cvt_pk_bf16_f32 v82, v82, v83
	v_cvt_pk_bf16_f32 v83, v84, v85
	v_cvt_pk_bf16_f32 v84, v86, v87
	v_cvt_pk_bf16_f32 v85, v88, v89
	v_cvt_pk_bf16_f32 v50, v50, v51
	v_cvt_pk_bf16_f32 v51, v52, v53
	v_cvt_pk_bf16_f32 v52, v54, v55
	v_cvt_pk_bf16_f32 v53, v56, v57
	s_waitcnt vmcnt(0)
	s_barrier
; DI unsigned pk2(float a, float b) { f32x2 v = {a, b}; bf2_t r = __builtin_convertvector(v, bf2_t); return __builtin_bit_cast(unsigned, r); }
;     ...
;   {
;     const int h = lane >> 5, cl = lane & 31;
; #pragma unroll
;     for (int i = 0; i < 2; ++i)
; #pragma unroll
;       for (int j = 0; j < 4; ++j)
; #pragma unroll
;         for (int g = 0; g < 4; ++g) {
;           u32x2 w; w.x = pk2(acc[i][j][4 * g], acc[i][j][4 * g + 1]); w.y = pk2(acc[i][j][4 * g + 2], acc[i][j][4 * g + 3]);
;           *(u32x2*)(smem + (wr * 64 + i * 32 + cl) * 528 + (wc * 128 + j * 32 + 8 * g + 4 * h) * 2) = w;
;         }
;   }
	ds_write2_b64 v0, v[114:115], v[116:117] offset1:2
	v_cvt_pk_bf16_f32 v114, v122, v123
	v_cvt_pk_bf16_f32 v115, v124, v125
	v_cvt_pk_bf16_f32 v116, v126, v127
	v_cvt_pk_bf16_f32 v117, v128, v129
	ds_write2_b64 v0, v[98:99], v[100:101] offset0:8 offset1:10
	v_cvt_pk_bf16_f32 v98, v106, v107
	v_cvt_pk_bf16_f32 v99, v108, v109
	v_cvt_pk_bf16_f32 v100, v110, v111
	v_cvt_pk_bf16_f32 v101, v112, v113
	ds_write2_b64 v0, v[82:83], v[84:85] offset0:16 offset1:18
	v_cvt_pk_bf16_f32 v82, v90, v91
	v_cvt_pk_bf16_f32 v83, v92, v93
	v_cvt_pk_bf16_f32 v84, v94, v95
	v_cvt_pk_bf16_f32 v85, v96, v97
	ds_write2_b64 v0, v[50:51], v[52:53] offset0:24 offset1:26
	v_cvt_pk_bf16_f32 v50, v58, v59
	v_cvt_pk_bf16_f32 v51, v60, v61
	v_cvt_pk_bf16_f32 v52, v62, v63
	v_cvt_pk_bf16_f32 v53, v64, v65
	ds_write2_b64 v0, v[114:115], v[116:117] offset0:4 offset1:6
	ds_write2_b64 v0, v[98:99], v[100:101] offset0:12 offset1:14
	ds_write2_b64 v0, v[82:83], v[84:85] offset0:20 offset1:22
	ds_write2_b64 v0, v[50:51], v[52:53] offset0:28 offset1:30
	v_cvt_pk_bf16_f32 v50, v66, v67
	v_cvt_pk_bf16_f32 v51, v68, v69
	v_cvt_pk_bf16_f32 v52, v70, v71
	v_cvt_pk_bf16_f32 v53, v72, v73
	v_add_u32_e32 v0, 0x4000, v0
	v_cvt_pk_bf16_f32 v34, v34, v35
	v_cvt_pk_bf16_f32 v35, v36, v37
	v_cvt_pk_bf16_f32 v36, v38, v39
	v_cvt_pk_bf16_f32 v37, v40, v41
	v_cvt_pk_bf16_f32 v18, v18, v19
	v_cvt_pk_bf16_f32 v19, v20, v21
	v_cvt_pk_bf16_f32 v20, v22, v23
	v_cvt_pk_bf16_f32 v21, v24, v25
	v_cvt_pk_bf16_f32 v2, v2, v3
	v_cvt_pk_bf16_f32 v3, v4, v5
	v_cvt_pk_bf16_f32 v4, v6, v7
	v_cvt_pk_bf16_f32 v5, v8, v9
	ds_write2_b64 v0, v[50:51], v[52:53] offset0:64 offset1:66
	v_cvt_pk_bf16_f32 v50, v74, v75
	v_cvt_pk_bf16_f32 v51, v76, v77
	v_cvt_pk_bf16_f32 v52, v78, v79
	v_cvt_pk_bf16_f32 v53, v80, v81
	ds_write2_b64 v0, v[34:35], v[36:37] offset0:72 offset1:74
	v_cvt_pk_bf16_f32 v34, v42, v43
	v_cvt_pk_bf16_f32 v35, v44, v45
	v_cvt_pk_bf16_f32 v36, v46, v47
	v_cvt_pk_bf16_f32 v37, v48, v49
	ds_write2_b64 v0, v[18:19], v[20:21] offset0:80 offset1:82
	v_cvt_pk_bf16_f32 v18, v26, v27
	v_cvt_pk_bf16_f32 v19, v28, v29
	v_cvt_pk_bf16_f32 v20, v30, v31
	v_cvt_pk_bf16_f32 v21, v32, v33
	ds_write2_b64 v0, v[2:3], v[4:5] offset0:88 offset1:90
	v_cvt_pk_bf16_f32 v2, v10, v11
	v_cvt_pk_bf16_f32 v3, v12, v13
	v_cvt_pk_bf16_f32 v4, v14, v15
	v_cvt_pk_bf16_f32 v5, v16, v17
	s_lshl_b64 s[14:15], s[14:15], 1
	ds_write2_b64 v0, v[50:51], v[52:53] offset0:68 offset1:70
	ds_write2_b64 v0, v[34:35], v[36:37] offset0:76 offset1:78
	ds_write2_b64 v0, v[18:19], v[20:21] offset0:84 offset1:86
	ds_write2_b64 v0, v[2:3], v[4:5] offset0:92 offset1:94
	s_waitcnt vmcnt(0) lgkmcnt(0)
	s_barrier
; #define GAS __attribute__((address_space(1)))
;     ...
;   int tid2 = tid; asm volatile("" : "+v"(tid2));
;   if (EPI == 0) {
; #pragma unroll
;     for (int i = 0; i < 16; ++i) {
;       const int id = tid2 + 256 * i, r = id >> 5, c8 = (id & 31) * 8;
;       const u32x4 v = *(const u32x4*)(smem + r * 528 + c8 * 2);
;       *(GAS u32x4*)(ea.out + (size_t)(m0 + r) * ea.ldo + n0 + c8) = v;
;     }
	s_add_u32 s14, s16, s14
	v_lshlrev_b32_e32 v0, 4, v189
	v_and_b32_e32 v0, 0x1f0, v0
	s_addc_u32 s15, s17, s15
	v_add_u32_e32 v10, 16, v0
	v_lshl_add_u64 v[12:13], s[14:15], 0, v[0:1]
	v_ashrrev_i32_e32 v0, 5, v189
	v_mad_u64_u32 v[2:3], s[14:15], v0, s55, v[10:11]
	v_add_u32_e32 v0, s12, v0
	v_mad_i64_i32 v[14:15], s[14:15], v0, s35, v[12:13]
	v_add_u32_e32 v0, 0x100, v189
	ds_read_b128 v[2:5], v2
	v_ashrrev_i32_e32 v0, 5, v0
	v_mad_u64_u32 v[6:7], s[14:15], v0, s55, v[10:11]
	ds_read_b128 v[6:9], v6
	v_add_u32_e32 v0, s12, v0
	s_waitcnt lgkmcnt(1)
	global_store_dwordx4 v[14:15], v[2:5], off nt
	v_readlane_b32 s10, v252, 12
	s_add_i32 s20, s20, s10
	v_mad_i64_i32 v[2:3], s[14:15], v0, s35, v[12:13]
	v_add_u32_e32 v0, 0x200, v189
	v_ashrrev_i32_e32 v0, 5, v0
	s_waitcnt lgkmcnt(0)
	global_store_dwordx4 v[2:3], v[6:9], off nt
	v_mad_u64_u32 v[2:3], s[14:15], v0, s55, v[10:11]
	v_add_u32_e32 v0, s12, v0
	v_mad_i64_i32 v[14:15], s[14:15], v0, s35, v[12:13]
	v_add_u32_e32 v0, 0x300, v189
	ds_read_b128 v[2:5], v2
	v_ashrrev_i32_e32 v0, 5, v0
	v_mad_u64_u32 v[6:7], s[14:15], v0, s55, v[10:11]
	ds_read_b128 v[6:9], v6
	v_add_u32_e32 v0, s12, v0
	s_waitcnt lgkmcnt(1)
	global_store_dwordx4 v[14:15], v[2:5], off nt
	s_cmp_ge_i32 s20, s45
	s_nop 0
	v_mad_i64_i32 v[2:3], s[14:15], v0, s35, v[12:13]
	v_add_u32_e32 v0, 0x400, v189
	v_ashrrev_i32_e32 v0, 5, v0
	s_waitcnt lgkmcnt(0)
	global_store_dwordx4 v[2:3], v[6:9], off nt
	v_mad_u64_u32 v[2:3], s[14:15], v0, s55, v[10:11]
	v_add_u32_e32 v0, s12, v0
	v_mad_i64_i32 v[14:15], s[14:15], v0, s35, v[12:13]
	v_add_u32_e32 v0, 0x500, v189
	ds_read_b128 v[2:5], v2
	v_ashrrev_i32_e32 v0, 5, v0
	v_mad_u64_u32 v[6:7], s[14:15], v0, s55, v[10:11]
	ds_read_b128 v[6:9], v6
	v_add_u32_e32 v0, s12, v0
	s_waitcnt lgkmcnt(1)
	global_store_dwordx4 v[14:15], v[2:5], off nt
	s_nop 1
	v_mad_i64_i32 v[2:3], s[14:15], v0, s35, v[12:13]
	v_add_u32_e32 v0, 0x600, v189
	v_ashrrev_i32_e32 v0, 5, v0
	s_waitcnt lgkmcnt(0)
	global_store_dwordx4 v[2:3], v[6:9], off nt
	v_mad_u64_u32 v[2:3], s[14:15], v0, s55, v[10:11]
	v_add_u32_e32 v0, s12, v0
	v_mad_i64_i32 v[14:15], s[14:15], v0, s35, v[12:13]
	v_add_u32_e32 v0, 0x700, v189
	ds_read_b128 v[2:5], v2
	v_ashrrev_i32_e32 v0, 5, v0
	v_mad_u64_u32 v[6:7], s[14:15], v0, s55, v[10:11]
	ds_read_b128 v[6:9], v6
	v_add_u32_e32 v0, s12, v0
	s_waitcnt lgkmcnt(1)
	global_store_dwordx4 v[14:15], v[2:5], off nt
	s_nop 1
	v_mad_i64_i32 v[2:3], s[14:15], v0, s35, v[12:13]
	v_add_u32_e32 v0, 0x800, v189
	v_ashrrev_i32_e32 v0, 5, v0
	s_waitcnt lgkmcnt(0)
	global_store_dwordx4 v[2:3], v[6:9], off nt
	v_mad_u64_u32 v[2:3], s[14:15], v0, s55, v[10:11]
	v_add_u32_e32 v0, s12, v0
	v_mad_i64_i32 v[14:15], s[14:15], v0, s35, v[12:13]
	v_add_u32_e32 v0, 0x900, v189
	ds_read_b128 v[2:5], v2
	v_ashrrev_i32_e32 v0, 5, v0
	v_mad_u64_u32 v[6:7], s[14:15], v0, s55, v[10:11]
	ds_read_b128 v[6:9], v6
	v_add_u32_e32 v0, s12, v0
	s_waitcnt lgkmcnt(1)
	global_store_dwordx4 v[14:15], v[2:5], off nt
	s_nop 1
	v_mad_i64_i32 v[2:3], s[14:15], v0, s35, v[12:13]
	v_add_u32_e32 v0, 0xa00, v189
	v_ashrrev_i32_e32 v0, 5, v0
	s_waitcnt lgkmcnt(0)
	global_store_dwordx4 v[2:3], v[6:9], off nt
	v_mad_u64_u32 v[2:3], s[14:15], v0, s55, v[10:11]
	v_add_u32_e32 v0, s12, v0
	v_mad_i64_i32 v[14:15], s[14:15], v0, s35, v[12:13]
	v_add_u32_e32 v0, 0xb00, v189
	ds_read_b128 v[2:5], v2
	v_ashrrev_i32_e32 v0, 5, v0
	v_mad_u64_u32 v[6:7], s[14:15], v0, s55, v[10:11]
	ds_read_b128 v[6:9], v6
	v_add_u32_e32 v0, s12, v0
	s_waitcnt lgkmcnt(1)
	global_store_dwordx4 v[14:15], v[2:5], off nt
	s_nop 1
	v_mad_i64_i32 v[2:3], s[14:15], v0, s35, v[12:13]
	v_add_u32_e32 v0, 0xc00, v189
	v_ashrrev_i32_e32 v0, 5, v0
	s_waitcnt lgkmcnt(0)
	global_store_dwordx4 v[2:3], v[6:9], off nt
	v_mad_u64_u32 v[2:3], s[14:15], v0, s55, v[10:11]
	v_add_u32_e32 v0, s12, v0
	v_mad_i64_i32 v[14:15], s[14:15], v0, s35, v[12:13]
	v_add_u32_e32 v0, 0xd00, v189
	ds_read_b128 v[2:5], v2
	v_ashrrev_i32_e32 v0, 5, v0
	v_mad_u64_u32 v[6:7], s[14:15], v0, s55, v[10:11]
	ds_read_b128 v[6:9], v6
	v_add_u32_e32 v0, s12, v0
	s_waitcnt lgkmcnt(1)
	global_store_dwordx4 v[14:15], v[2:5], off nt
	s_nop 1
	v_mad_i64_i32 v[2:3], s[14:15], v0, s35, v[12:13]
	v_add_u32_e32 v0, 0xe00, v189
	v_ashrrev_i32_e32 v0, 5, v0
	s_waitcnt lgkmcnt(0)
	global_store_dwordx4 v[2:3], v[6:9], off nt
	v_mad_u64_u32 v[2:3], s[14:15], v0, s55, v[10:11]
	v_add_u32_e32 v0, s12, v0
	v_mad_i64_i32 v[14:15], s[14:15], v0, s35, v[12:13]
	v_add_u32_e32 v0, 0xf00, v189
	v_ashrrev_i32_e32 v0, 5, v0
	ds_read_b128 v[2:5], v2
	v_mad_u64_u32 v[6:7], s[14:15], v0, s55, v[10:11]
	ds_read_b128 v[6:9], v6
	v_add_u32_e32 v0, s12, v0
	s_waitcnt lgkmcnt(1)
	global_store_dwordx4 v[14:15], v[2:5], off nt
	s_nop 1
	v_mad_i64_i32 v[2:3], s[12:13], v0, s35, v[12:13]
	s_waitcnt lgkmcnt(0)
	global_store_dwordx4 v[2:3], v[6:9], off nt
	s_barrier
	s_cbranch_scc0 .LBB0_183
	v_mov_b64_e32 v[6:7], v[130:131]
	v_mov_b64_e32 v[2:3], v[134:135]
	v_mov_b32_e32 v31, v214
	v_mov_b32_e32 v30, v215
	v_mov_b32_e32 v29, v216
	v_mov_b32_e32 v28, v217
	v_mov_b64_e32 v[8:9], v[132:133]
	v_mov_b64_e32 v[4:5], v[136:137]
	v_readlane_b32 s44, v250, 17

; #define LAS __attribute__((address_space(3)))
; DI f32x16 mfma32(bf16x8 a, bf16x8 b, f32x16 c) { return __builtin_amdgcn_mfma_f32_32x32x16_bf16(a, b, c, 0, 0, 0); }
;     ...
;   for (int kt = 0; kt < nk; ++kt) {
;     const int kn = (kt + 2 < nk) ? (kt + 2) : (nk - 1);
;     const LAS char* cur = lds + s0;
;     bf16x8 af[2][2], bfr[2][4];
; #pragma unroll
;     for (int kk = 0; kk < 2; ++kk) {
;       const int xo = kk ? x1 : x0;
;       af[kk][0] = *(const LAS bf16x8*)(cur + a_rd + xo);
;       bfr[kk][0] = *(const LAS bf16x8*)(cur + b_rd + xo);
;       bfr[kk][1] = *(const LAS bf16x8*)(cur + b_rd + 2048 + xo);
;       af[kk][1] = *(const LAS bf16x8*)(cur + a_rd + 2048 + xo);
;       bfr[kk][2] = *(const LAS bf16x8*)(cur + b_rd + 4096 + xo);
;       bfr[kk][3] = *(const LAS bf16x8*)(cur + b_rd + 6144 + xo);
;     }
;     DMA_STEP_(kn, s2);
; #pragma unroll
;     for (int kk = 0; kk < 2; ++kk) {
;       acc[0][0] = mfma32(bfr[kk][0], af[kk][0], acc[0][0]); acc[0][1] = mfma32(bfr[kk][1], af[kk][0], acc[0][1]);
;       acc[1][0] = mfma32(bfr[kk][0], af[kk][1], acc[1][0]); acc[1][1] = mfma32(bfr[kk][1], af[kk][1], acc[1][1]);
;       acc[0][2] = mfma32(bfr[kk][2], af[kk][0], acc[0][2]); acc[0][3] = mfma32(bfr[kk][3], af[kk][0], acc[0][3]);
;       acc[1][2] = mfma32(bfr[kk][2], af[kk][1], acc[1][2]); acc[1][3] = mfma32(bfr[kk][3], af[kk][1], acc[1][3]);
;     }
;     __builtin_amdgcn_sched_group_barrier(0x100, 12, 0);
;     __builtin_amdgcn_sched_group_barrier(0x010, 6, 0);
;     __builtin_amdgcn_sched_group_barrier(0x008, 16, 0);
;     asm volatile("s_waitcnt vmcnt(6) lgkmcnt(0)" ::: "memory");
;     __builtin_amdgcn_s_barrier();
;     asm volatile("" ::: "memory");
;     s0 = (s0 == 2 * STG) ? 0 : s0 + STG;
;     s2 = (s2 == 2 * STG) ? 0 : s2 + STG;
;   }
.LBB0_235:
	s_add_i32 s11, s41, 16
	s_mov_b32 s10, s29
	v_add_u32_e32 v142, s11, v219
	v_add_u32_e32 v150, s11, v218
	s_min_u32 s10, s10, 29
	v_add_u32_e32 v142, v142, v220
	v_add_u32_e32 v150, v150, v220
	s_lshl_b32 s70, s10, 6
	ds_read_b128 v[138:141], v142
	ds_read_b128 v[162:165], v150 offset:8192
	ds_read_b128 v[166:169], v150 offset:10240
	ds_read_b128 v[142:145], v142 offset:2048
	ds_read_b128 v[146:149], v150 offset:12288
	ds_read_b128 v[150:153], v150 offset:14336
	s_mul_i32 vcc_lo, s70, 0x12000
	s_add_i32 s10, s13, s40
	v_lshl_add_u64 v[222:223], v[192:193], 0, vcc
	s_mov_b32 m0, s10
	s_mul_i32 s100, s70, 0x900
	v_lshl_add_u64 v[224:225], v[194:195], 0, s[100:101]
	s_add_i32 s10, s28, s40
	s_waitcnt lgkmcnt(6)
	v_mfma_f32_32x32x16_bf16 v[114:129], v[182:185], v[154:157], v[114:129]
	global_load_lds_dwordx4 v[222:223], off
	v_mfma_f32_32x32x16_bf16 v[98:113], v[178:181], v[154:157], v[98:113]
	global_load_lds_dwordx4 v[222:223], off offset:1024
	s_add_i32 m0, s10, 0x2000
	v_mfma_f32_32x32x16_bf16 v[66:81], v[182:185], v[158:161], v[66:81]
	global_load_lds_dwordx4 v[224:225], off
	v_mfma_f32_32x32x16_bf16 v[34:49], v[178:181], v[158:161], v[34:49]
	global_load_lds_dwordx4 v[224:225], off offset:1024
	v_mfma_f32_32x32x16_bf16 v[82:97], v[174:177], v[154:157], v[82:97]
	global_load_lds_dwordx4 v[224:225], off offset:2048
	v_mfma_f32_32x32x16_bf16 v[50:65], v[170:173], v[154:157], v[50:65]
	global_load_lds_dwordx4 v[224:225], off offset:3072
	v_mfma_f32_32x32x16_bf16 v[18:33], v[174:177], v[158:161], v[18:33]
	s_add_i32 s10, s41, 0x6000
	s_cmpk_lg_u32 s41, 0xc000
	s_cselect_b32 s41, s10, 0
	s_add_i32 s10, s40, 0x6000
	s_cmpk_lg_u32 s40, 0xc000
	s_cselect_b32 s40, s10, 0
	v_mfma_f32_32x32x16_bf16 v[2:17], v[170:173], v[158:161], v[2:17]
	s_add_i32 s11, s41, 16
	s_waitcnt vmcnt(6) lgkmcnt(0)
	s_barrier
	v_add_u32_e32 v158, s11, v219
	v_add_u32_e32 v170, s11, v218
	v_add_u32_e32 v158, v158, v0
	v_add_u32_e32 v170, v170, v0
	ds_read_b128 v[154:157], v158
	ds_read_b128 v[182:185], v170 offset:8192
	ds_read_b128 v[178:181], v170 offset:10240
	ds_read_b128 v[158:161], v158 offset:2048
	ds_read_b128 v[174:177], v170 offset:12288
	ds_read_b128 v[170:173], v170 offset:14336
	v_mfma_f32_32x32x16_bf16 v[114:129], v[162:165], v[138:141], v[114:129]
	v_mfma_f32_32x32x16_bf16 v[98:113], v[166:169], v[138:141], v[98:113]
	v_mfma_f32_32x32x16_bf16 v[66:81], v[162:165], v[142:145], v[66:81]
	v_mfma_f32_32x32x16_bf16 v[34:49], v[166:169], v[142:145], v[34:49]
	v_mfma_f32_32x32x16_bf16 v[82:97], v[146:149], v[138:141], v[82:97]
	v_mfma_f32_32x32x16_bf16 v[50:65], v[150:153], v[138:141], v[50:65]
	v_mfma_f32_32x32x16_bf16 v[18:33], v[146:149], v[142:145], v[18:33]
	v_mfma_f32_32x32x16_bf16 v[2:17], v[150:153], v[142:145], v[2:17]
	s_add_i32 s11, s41, 16
	s_add_i32 s10, s29, 1
	v_add_u32_e32 v142, s11, v219
	v_add_u32_e32 v150, s11, v218
	s_min_u32 s10, s10, 29
	v_add_u32_e32 v142, v142, v220
	v_add_u32_e32 v150, v150, v220
	s_lshl_b32 s70, s10, 6
	ds_read_b128 v[138:141], v142
	ds_read_b128 v[162:165], v150 offset:8192
	ds_read_b128 v[166:169], v150 offset:10240
	ds_read_b128 v[142:145], v142 offset:2048
	ds_read_b128 v[146:149], v150 offset:12288
	ds_read_b128 v[150:153], v150 offset:14336
	s_mul_i32 vcc_lo, s70, 0x12000
	s_add_i32 s10, s13, s40
	v_lshl_add_u64 v[222:223], v[192:193], 0, vcc
	s_mov_b32 m0, s10
	s_mul_i32 s100, s70, 0x900
	v_lshl_add_u64 v[224:225], v[194:195], 0, s[100:101]
	s_add_i32 s10, s28, s40
	s_waitcnt lgkmcnt(6)
	v_mfma_f32_32x32x16_bf16 v[114:129], v[182:185], v[154:157], v[114:129]
	global_load_lds_dwordx4 v[222:223], off
	v_mfma_f32_32x32x16_bf16 v[98:113], v[178:181], v[154:157], v[98:113]
	global_load_lds_dwordx4 v[222:223], off offset:1024
	s_add_i32 m0, s10, 0x2000
	v_mfma_f32_32x32x16_bf16 v[66:81], v[182:185], v[158:161], v[66:81]
	global_load_lds_dwordx4 v[224:225], off
	v_mfma_f32_32x32x16_bf16 v[34:49], v[178:181], v[158:161], v[34:49]
	global_load_lds_dwordx4 v[224:225], off offset:1024
	v_mfma_f32_32x32x16_bf16 v[82:97], v[174:177], v[154:157], v[82:97]
	global_load_lds_dwordx4 v[224:225], off offset:2048
	v_mfma_f32_32x32x16_bf16 v[50:65], v[170:173], v[154:157], v[50:65]
	global_load_lds_dwordx4 v[224:225], off offset:3072
	v_mfma_f32_32x32x16_bf16 v[18:33], v[174:177], v[158:161], v[18:33]
	s_add_i32 s10, s41, 0x6000
	s_cmpk_lg_u32 s41, 0xc000
	s_cselect_b32 s41, s10, 0
	s_add_i32 s10, s40, 0x6000
	s_cmpk_lg_u32 s40, 0xc000
	s_cselect_b32 s40, s10, 0
	v_mfma_f32_32x32x16_bf16 v[2:17], v[170:173], v[158:161], v[2:17]
	s_add_i32 s11, s41, 16
	s_waitcnt vmcnt(6) lgkmcnt(0)
	s_barrier
	v_add_u32_e32 v158, s11, v219
	v_add_u32_e32 v170, s11, v218
	v_add_u32_e32 v158, v158, v0
	v_add_u32_e32 v170, v170, v0
	ds_read_b128 v[154:157], v158
	ds_read_b128 v[182:185], v170 offset:8192
	ds_read_b128 v[178:181], v170 offset:10240
	ds_read_b128 v[158:161], v158 offset:2048
	ds_read_b128 v[174:177], v170 offset:12288
	ds_read_b128 v[170:173], v170 offset:14336
	v_mfma_f32_32x32x16_bf16 v[114:129], v[162:165], v[138:141], v[114:129]
	v_mfma_f32_32x32x16_bf16 v[98:113], v[166:169], v[138:141], v[98:113]
	v_mfma_f32_32x32x16_bf16 v[66:81], v[162:165], v[142:145], v[66:81]
	v_mfma_f32_32x32x16_bf16 v[34:49], v[166:169], v[142:145], v[34:49]
	v_mfma_f32_32x32x16_bf16 v[82:97], v[146:149], v[138:141], v[82:97]
	v_mfma_f32_32x32x16_bf16 v[50:65], v[150:153], v[138:141], v[50:65]
	v_mfma_f32_32x32x16_bf16 v[18:33], v[146:149], v[142:145], v[18:33]
	v_mfma_f32_32x32x16_bf16 v[2:17], v[150:153], v[142:145], v[2:17]
	s_add_i32 s29, s29, 2
	s_cmp_lg_u32 s29, 30
	s_cbranch_scc1 .LBB0_235
; #define LAS __attribute__((address_space(3)))
; DI unsigned pk2(float a, float b) { f32x2 v = {a, b}; bf2_t r = __builtin_convertvector(v, bf2_t); return __builtin_bit_cast(unsigned, r); }
; DI f32x16 mfma32(bf16x8 a, bf16x8 b, f32x16 c) { return __builtin_amdgcn_mfma_f32_32x32x16_bf16(a, b, c, 0, 0, 0); }
;     ...
;   for (int kt = 0; kt < nk; ++kt) {
;     const int kn = (kt + 2 < nk) ? (kt + 2) : (nk - 1);
;     const LAS char* cur = lds + s0;
;     bf16x8 af[2][2], bfr[2][4];
; #pragma unroll
;     for (int kk = 0; kk < 2; ++kk) {
;       const int xo = kk ? x1 : x0;
;       af[kk][0] = *(const LAS bf16x8*)(cur + a_rd + xo);
;       bfr[kk][0] = *(const LAS bf16x8*)(cur + b_rd + xo);
;       bfr[kk][1] = *(const LAS bf16x8*)(cur + b_rd + 2048 + xo);
;       af[kk][1] = *(const LAS bf16x8*)(cur + a_rd + 2048 + xo);
;       bfr[kk][2] = *(const LAS bf16x8*)(cur + b_rd + 4096 + xo);
;       bfr[kk][3] = *(const LAS bf16x8*)(cur + b_rd + 6144 + xo);
;     }
;     DMA_STEP_(kn, s2);
; #pragma unroll
;     for (int kk = 0; kk < 2; ++kk) {
;       acc[0][0] = mfma32(bfr[kk][0], af[kk][0], acc[0][0]); acc[0][1] = mfma32(bfr[kk][1], af[kk][0], acc[0][1]);
;       acc[1][0] = mfma32(bfr[kk][0], af[kk][1], acc[1][0]); acc[1][1] = mfma32(bfr[kk][1], af[kk][1], acc[1][1]);
;       acc[0][2] = mfma32(bfr[kk][2], af[kk][0], acc[0][2]); acc[0][3] = mfma32(bfr[kk][3], af[kk][0], acc[0][3]);
;       acc[1][2] = mfma32(bfr[kk][2], af[kk][1], acc[1][2]); acc[1][3] = mfma32(bfr[kk][3], af[kk][1], acc[1][3]);
;     }
;     __builtin_amdgcn_sched_group_barrier(0x100, 12, 0);
;     __builtin_amdgcn_sched_group_barrier(0x010, 6, 0);
;     __builtin_amdgcn_sched_group_barrier(0x008, 16, 0);
;     asm volatile("s_waitcnt vmcnt(6) lgkmcnt(0)" ::: "memory");
;     __builtin_amdgcn_s_barrier();
;     asm volatile("" ::: "memory");
;     s0 = (s0 == 2 * STG) ? 0 : s0 + STG;
;     s2 = (s2 == 2 * STG) ? 0 : s2 + STG;
;   }
;     ...
;   {
;     const int h = lane >> 5, cl = lane & 31;
; #pragma unroll
;     for (int i = 0; i < 2; ++i)
; #pragma unroll
;       for (int j = 0; j < 4; ++j)
; #pragma unroll
;         for (int g = 0; g < 4; ++g) {
;           u32x2 w; w.x = pk2(acc[i][j][4 * g], acc[i][j][4 * g + 1]); w.y = pk2(acc[i][j][4 * g + 2], acc[i][j][4 * g + 3]);
;           *(u32x2*)(smem + (wr * 64 + i * 32 + cl) * 528 + (wc * 128 + j * 32 + 8 * g + 4 * h) * 2) = w;
;         }
;   }
	s_add_i32 s11, s41, 16
	v_add_u32_e32 v142, s11, v219
	v_add_u32_e32 v150, s11, v218
	v_add_u32_e32 v142, v142, v220
	v_add_u32_e32 v150, v150, v220
	ds_read_b128 v[138:141], v142
	ds_read_b128 v[162:165], v150 offset:8192
	ds_read_b128 v[166:169], v150 offset:10240
	ds_read_b128 v[142:145], v142 offset:2048
	ds_read_b128 v[146:149], v150 offset:12288
	ds_read_b128 v[150:153], v150 offset:14336
	s_waitcnt lgkmcnt(6)
	v_mfma_f32_32x32x16_bf16 v[114:129], v[182:185], v[154:157], v[114:129]
	v_mfma_f32_32x32x16_bf16 v[98:113], v[178:181], v[154:157], v[98:113]
	v_mfma_f32_32x32x16_bf16 v[66:81], v[182:185], v[158:161], v[66:81]
	v_mfma_f32_32x32x16_bf16 v[34:49], v[178:181], v[158:161], v[34:49]
	v_mfma_f32_32x32x16_bf16 v[82:97], v[174:177], v[154:157], v[82:97]
	v_mfma_f32_32x32x16_bf16 v[50:65], v[170:173], v[154:157], v[50:65]
	v_mfma_f32_32x32x16_bf16 v[18:33], v[174:177], v[158:161], v[18:33]
	s_add_i32 s10, s41, 0x6000
	s_cmpk_lg_u32 s41, 0xc000
	s_cselect_b32 s41, s10, 0
	v_mfma_f32_32x32x16_bf16 v[2:17], v[170:173], v[158:161], v[2:17]
	s_add_i32 s11, s41, 16
	s_waitcnt vmcnt(0) lgkmcnt(0)
	s_barrier
	v_add_u32_e32 v158, s11, v219
	v_add_u32_e32 v170, s11, v218
	v_add_u32_e32 v158, v158, v0
	v_add_u32_e32 v170, v170, v0
	ds_read_b128 v[154:157], v158
	ds_read_b128 v[182:185], v170 offset:8192
	ds_read_b128 v[178:181], v170 offset:10240
	ds_read_b128 v[158:161], v158 offset:2048
	ds_read_b128 v[174:177], v170 offset:12288
	ds_read_b128 v[170:173], v170 offset:14336
	v_mfma_f32_32x32x16_bf16 v[114:129], v[162:165], v[138:141], v[114:129]
	v_mfma_f32_32x32x16_bf16 v[98:113], v[166:169], v[138:141], v[98:113]
	v_mfma_f32_32x32x16_bf16 v[66:81], v[162:165], v[142:145], v[66:81]
	v_mfma_f32_32x32x16_bf16 v[34:49], v[166:169], v[142:145], v[34:49]
	v_mfma_f32_32x32x16_bf16 v[82:97], v[146:149], v[138:141], v[82:97]
	v_mfma_f32_32x32x16_bf16 v[50:65], v[150:153], v[138:141], v[50:65]
	v_mfma_f32_32x32x16_bf16 v[18:33], v[146:149], v[142:145], v[18:33]
	v_mfma_f32_32x32x16_bf16 v[2:17], v[150:153], v[142:145], v[2:17]
	s_add_i32 s11, s41, 16
	v_add_u32_e32 v142, s11, v219
	v_add_u32_e32 v150, s11, v218
	v_add_u32_e32 v142, v142, v220
	v_add_u32_e32 v150, v150, v220
	ds_read_b128 v[138:141], v142
	ds_read_b128 v[162:165], v150 offset:8192
	ds_read_b128 v[166:169], v150 offset:10240
	ds_read_b128 v[142:145], v142 offset:2048
	ds_read_b128 v[146:149], v150 offset:12288
	ds_read_b128 v[150:153], v150 offset:14336
	s_waitcnt lgkmcnt(6)
	v_mfma_f32_32x32x16_bf16 v[114:129], v[182:185], v[154:157], v[114:129]
	v_mfma_f32_32x32x16_bf16 v[98:113], v[178:181], v[154:157], v[98:113]
	v_mfma_f32_32x32x16_bf16 v[66:81], v[182:185], v[158:161], v[66:81]
	v_mfma_f32_32x32x16_bf16 v[34:49], v[178:181], v[158:161], v[34:49]
	v_mfma_f32_32x32x16_bf16 v[82:97], v[174:177], v[154:157], v[82:97]
	v_mfma_f32_32x32x16_bf16 v[50:65], v[170:173], v[154:157], v[50:65]
	v_mfma_f32_32x32x16_bf16 v[18:33], v[174:177], v[158:161], v[18:33]
	v_mfma_f32_32x32x16_bf16 v[2:17], v[170:173], v[158:161], v[2:17]
	s_waitcnt lgkmcnt(0)
	v_mfma_f32_32x32x16_bf16 v[114:129], v[162:165], v[138:141], v[114:129]
	v_mfma_f32_32x32x16_bf16 v[98:113], v[166:169], v[138:141], v[98:113]
	v_mfma_f32_32x32x16_bf16 v[66:81], v[162:165], v[142:145], v[66:81]
	v_mfma_f32_32x32x16_bf16 v[34:49], v[166:169], v[142:145], v[34:49]
	v_mfma_f32_32x32x16_bf16 v[82:97], v[146:149], v[138:141], v[82:97]
	v_mfma_f32_32x32x16_bf16 v[50:65], v[150:153], v[138:141], v[50:65]
	v_mfma_f32_32x32x16_bf16 v[18:33], v[146:149], v[142:145], v[18:33]
	v_mfma_f32_32x32x16_bf16 v[2:17], v[150:153], v[142:145], v[2:17]
	s_waitcnt lgkmcnt(0)
	s_setprio 0
	v_mul_lo_u32 v0, v197, s55
	v_add_u32_e32 v0, 16, v0
	s_nop 1
	v_cvt_pk_bf16_f32 v114, v114, v115
	v_cvt_pk_bf16_f32 v115, v116, v117
	v_lshlrev_b32_e32 v116, 3, v196
	s_lshl_b32 s10, s23, 1
	v_add3_u32 v0, v0, v116, s10
	v_cvt_pk_bf16_f32 v116, v118, v119
	v_cvt_pk_bf16_f32 v117, v120, v121
	v_cvt_pk_bf16_f32 v98, v98, v99
	v_cvt_pk_bf16_f32 v99, v100, v101
	v_cvt_pk_bf16_f32 v100, v102, v103
	v_cvt_pk_bf16_f32 v101, v104, v105
	v_cvt_pk_bf16_f32 v82, v82, v83
	v_cvt_pk_bf16_f32 v83, v84, v85
	v_cvt_pk_bf16_f32 v84, v86, v87
	v_cvt_pk_bf16_f32 v85, v88, v89
	v_cvt_pk_bf16_f32 v50, v50, v51
	v_cvt_pk_bf16_f32 v51, v52, v53
	v_cvt_pk_bf16_f32 v52, v54, v55
	v_cvt_pk_bf16_f32 v53, v56, v57
	s_waitcnt vmcnt(0)
	s_barrier
; DI unsigned pk2(float a, float b) { f32x2 v = {a, b}; bf2_t r = __builtin_convertvector(v, bf2_t); return __builtin_bit_cast(unsigned, r); }
;     ...
;   {
;     const int h = lane >> 5, cl = lane & 31;
; #pragma unroll
;     for (int i = 0; i < 2; ++i)
; #pragma unroll
;       for (int j = 0; j < 4; ++j)
; #pragma unroll
;         for (int g = 0; g < 4; ++g) {
;           u32x2 w; w.x = pk2(acc[i][j][4 * g], acc[i][j][4 * g + 1]); w.y = pk2(acc[i][j][4 * g + 2], acc[i][j][4 * g + 3]);
;           *(u32x2*)(smem + (wr * 64 + i * 32 + cl) * 528 + (wc * 128 + j * 32 + 8 * g + 4 * h) * 2) = w;
;         }
;   }
	ds_write2_b64 v0, v[114:115], v[116:117] offset1:2
	v_cvt_pk_bf16_f32 v114, v122, v123
	v_cvt_pk_bf16_f32 v115, v124, v125
	v_cvt_pk_bf16_f32 v116, v126, v127
	v_cvt_pk_bf16_f32 v117, v128, v129
	ds_write2_b64 v0, v[98:99], v[100:101] offset0:8 offset1:10
	v_cvt_pk_bf16_f32 v98, v106, v107
	v_cvt_pk_bf16_f32 v99, v108, v109
	v_cvt_pk_bf16_f32 v100, v110, v111
	v_cvt_pk_bf16_f32 v101, v112, v113
	ds_write2_b64 v0, v[82:83], v[84:85] offset0:16 offset1:18
	v_cvt_pk_bf16_f32 v82, v90, v91
	v_cvt_pk_bf16_f32 v83, v92, v93
	v_cvt_pk_bf16_f32 v84, v94, v95
	v_cvt_pk_bf16_f32 v85, v96, v97
	ds_write2_b64 v0, v[50:51], v[52:53] offset0:24 offset1:26
	v_cvt_pk_bf16_f32 v50, v58, v59
	v_cvt_pk_bf16_f32 v51, v60, v61
	v_cvt_pk_bf16_f32 v52, v62, v63
	v_cvt_pk_bf16_f32 v53, v64, v65
	ds_write2_b64 v0, v[114:115], v[116:117] offset0:4 offset1:6
	ds_write2_b64 v0, v[98:99], v[100:101] offset0:12 offset1:14
	ds_write2_b64 v0, v[82:83], v[84:85] offset0:20 offset1:22
	ds_write2_b64 v0, v[50:51], v[52:53] offset0:28 offset1:30
	v_cvt_pk_bf16_f32 v50, v66, v67
	v_cvt_pk_bf16_f32 v51, v68, v69
	v_cvt_pk_bf16_f32 v52, v70, v71
	v_cvt_pk_bf16_f32 v53, v72, v73
	v_add_u32_e32 v0, 0x4000, v0
	v_cvt_pk_bf16_f32 v34, v34, v35
	v_cvt_pk_bf16_f32 v35, v36, v37
	v_cvt_pk_bf16_f32 v36, v38, v39
	v_cvt_pk_bf16_f32 v37, v40, v41
	v_cvt_pk_bf16_f32 v18, v18, v19
	v_cvt_pk_bf16_f32 v19, v20, v21
	v_cvt_pk_bf16_f32 v20, v22, v23
	v_cvt_pk_bf16_f32 v21, v24, v25
	v_cvt_pk_bf16_f32 v2, v2, v3
	v_cvt_pk_bf16_f32 v3, v4, v5
	v_cvt_pk_bf16_f32 v4, v6, v7
	v_cvt_pk_bf16_f32 v5, v8, v9
	ds_write2_b64 v0, v[50:51], v[52:53] offset0:64 offset1:66
	v_cvt_pk_bf16_f32 v50, v74, v75
	v_cvt_pk_bf16_f32 v51, v76, v77
	v_cvt_pk_bf16_f32 v52, v78, v79
	v_cvt_pk_bf16_f32 v53, v80, v81
	ds_write2_b64 v0, v[34:35], v[36:37] offset0:72 offset1:74
	v_cvt_pk_bf16_f32 v34, v42, v43
	v_cvt_pk_bf16_f32 v35, v44, v45
	v_cvt_pk_bf16_f32 v36, v46, v47
	v_cvt_pk_bf16_f32 v37, v48, v49
	ds_write2_b64 v0, v[18:19], v[20:21] offset0:80 offset1:82
	v_cvt_pk_bf16_f32 v18, v26, v27
	v_cvt_pk_bf16_f32 v19, v28, v29
	v_cvt_pk_bf16_f32 v20, v30, v31
	v_cvt_pk_bf16_f32 v21, v32, v33
	ds_write2_b64 v0, v[2:3], v[4:5] offset0:88 offset1:90
	v_cvt_pk_bf16_f32 v2, v10, v11
	v_cvt_pk_bf16_f32 v3, v12, v13
	v_cvt_pk_bf16_f32 v4, v14, v15
	v_cvt_pk_bf16_f32 v5, v16, v17
	s_lshl_b64 s[10:11], s[14:15], 1
	ds_write2_b64 v0, v[50:51], v[52:53] offset0:68 offset1:70
	ds_write2_b64 v0, v[34:35], v[36:37] offset0:76 offset1:78
	ds_write2_b64 v0, v[18:19], v[20:21] offset0:84 offset1:86
	ds_write2_b64 v0, v[2:3], v[4:5] offset0:92 offset1:94
	s_waitcnt vmcnt(0) lgkmcnt(0)
	s_barrier
; #define GAS __attribute__((address_space(1)))
;     ...
;   int tid2 = tid; asm volatile("" : "+v"(tid2));
;   if (EPI == 0) {
; #pragma unroll
;     for (int i = 0; i < 16; ++i) {
;       const int id = tid2 + 256 * i, r = id >> 5, c8 = (id & 31) * 8;
;       const u32x4 v = *(const u32x4*)(smem + r * 528 + c8 * 2);
;       *(GAS u32x4*)(ea.out + (size_t)(m0 + r) * ea.ldo + n0 + c8) = v;
;     }
	s_add_u32 s10, s16, s10
	v_lshlrev_b32_e32 v0, 4, v189
	v_and_b32_e32 v0, 0x1f0, v0
	s_addc_u32 s11, s17, s11
	v_add_u32_e32 v10, 16, v0
	v_lshl_add_u64 v[12:13], s[10:11], 0, v[0:1]
	v_ashrrev_i32_e32 v0, 5, v189
	v_mad_u64_u32 v[2:3], s[10:11], v0, s55, v[10:11]
	v_add_u32_e32 v0, s12, v0
	v_mad_i64_i32 v[14:15], s[10:11], v0, s35, v[12:13]
	v_add_u32_e32 v0, 0x100, v189
	ds_read_b128 v[2:5], v2
	v_ashrrev_i32_e32 v0, 5, v0
	v_mad_u64_u32 v[6:7], s[10:11], v0, s55, v[10:11]
	ds_read_b128 v[6:9], v6
	v_add_u32_e32 v0, s12, v0
	s_waitcnt lgkmcnt(1)
	global_store_dwordx4 v[14:15], v[2:5], off nt
	s_nop 1
	v_mad_i64_i32 v[2:3], s[10:11], v0, s35, v[12:13]
	v_add_u32_e32 v0, 0x200, v189
	v_ashrrev_i32_e32 v0, 5, v0
	s_waitcnt lgkmcnt(0)
	global_store_dwordx4 v[2:3], v[6:9], off nt
	v_mad_u64_u32 v[2:3], s[10:11], v0, s55, v[10:11]
	v_add_u32_e32 v0, s12, v0
	v_mad_i64_i32 v[14:15], s[10:11], v0, s35, v[12:13]
	v_add_u32_e32 v0, 0x300, v189
	ds_read_b128 v[2:5], v2
	v_ashrrev_i32_e32 v0, 5, v0
	v_mad_u64_u32 v[6:7], s[10:11], v0, s55, v[10:11]
	ds_read_b128 v[6:9], v6
	v_add_u32_e32 v0, s12, v0
	s_waitcnt lgkmcnt(1)
	global_store_dwordx4 v[14:15], v[2:5], off nt
	s_nop 1
	v_mad_i64_i32 v[2:3], s[10:11], v0, s35, v[12:13]
	v_add_u32_e32 v0, 0x400, v189
	v_ashrrev_i32_e32 v0, 5, v0
	s_waitcnt lgkmcnt(0)
	global_store_dwordx4 v[2:3], v[6:9], off nt
	v_mad_u64_u32 v[2:3], s[10:11], v0, s55, v[10:11]
	v_add_u32_e32 v0, s12, v0
	v_mad_i64_i32 v[14:15], s[10:11], v0, s35, v[12:13]
	v_add_u32_e32 v0, 0x500, v189
	ds_read_b128 v[2:5], v2
	v_ashrrev_i32_e32 v0, 5, v0
	v_mad_u64_u32 v[6:7], s[10:11], v0, s55, v[10:11]
	ds_read_b128 v[6:9], v6
	v_add_u32_e32 v0, s12, v0
	s_waitcnt lgkmcnt(1)
	global_store_dwordx4 v[14:15], v[2:5], off nt
	s_nop 1
	v_mad_i64_i32 v[2:3], s[10:11], v0, s35, v[12:13]
	v_add_u32_e32 v0, 0x600, v189
	v_ashrrev_i32_e32 v0, 5, v0
	s_waitcnt lgkmcnt(0)
	global_store_dwordx4 v[2:3], v[6:9], off nt
	v_mad_u64_u32 v[2:3], s[10:11], v0, s55, v[10:11]
	v_add_u32_e32 v0, s12, v0
	v_mad_i64_i32 v[14:15], s[10:11], v0, s35, v[12:13]
	v_add_u32_e32 v0, 0x700, v189
	ds_read_b128 v[2:5], v2
	v_ashrrev_i32_e32 v0, 5, v0
	v_mad_u64_u32 v[6:7], s[10:11], v0, s55, v[10:11]
	ds_read_b128 v[6:9], v6
	v_add_u32_e32 v0, s12, v0
	s_waitcnt lgkmcnt(1)
	global_store_dwordx4 v[14:15], v[2:5], off nt
	s_nop 1
	v_mad_i64_i32 v[2:3], s[10:11], v0, s35, v[12:13]
	v_add_u32_e32 v0, 0x800, v189
	v_ashrrev_i32_e32 v0, 5, v0
	s_waitcnt lgkmcnt(0)
	global_store_dwordx4 v[2:3], v[6:9], off nt
	v_mad_u64_u32 v[2:3], s[10:11], v0, s55, v[10:11]
	v_add_u32_e32 v0, s12, v0
	v_mad_i64_i32 v[14:15], s[10:11], v0, s35, v[12:13]
	v_add_u32_e32 v0, 0x900, v189
	ds_read_b128 v[2:5], v2
	v_ashrrev_i32_e32 v0, 5, v0
	v_mad_u64_u32 v[6:7], s[10:11], v0, s55, v[10:11]
	ds_read_b128 v[6:9], v6
	v_add_u32_e32 v0, s12, v0
	s_waitcnt lgkmcnt(1)
	global_store_dwordx4 v[14:15], v[2:5], off nt
	s_nop 1
	v_mad_i64_i32 v[2:3], s[10:11], v0, s35, v[12:13]
	v_add_u32_e32 v0, 0xa00, v189
	v_ashrrev_i32_e32 v0, 5, v0
	s_waitcnt lgkmcnt(0)
	global_store_dwordx4 v[2:3], v[6:9], off nt
	v_mad_u64_u32 v[2:3], s[10:11], v0, s55, v[10:11]
	v_add_u32_e32 v0, s12, v0
	v_mad_i64_i32 v[14:15], s[10:11], v0, s35, v[12:13]
	v_add_u32_e32 v0, 0xb00, v189
	ds_read_b128 v[2:5], v2
	v_ashrrev_i32_e32 v0, 5, v0
	v_mad_u64_u32 v[6:7], s[10:11], v0, s55, v[10:11]
	ds_read_b128 v[6:9], v6
	v_add_u32_e32 v0, s12, v0
	s_waitcnt lgkmcnt(1)
	global_store_dwordx4 v[14:15], v[2:5], off nt
	s_nop 1
	v_mad_i64_i32 v[2:3], s[10:11], v0, s35, v[12:13]
	v_add_u32_e32 v0, 0xc00, v189
	v_ashrrev_i32_e32 v0, 5, v0
	s_waitcnt lgkmcnt(0)
	global_store_dwordx4 v[2:3], v[6:9], off nt
	v_mad_u64_u32 v[2:3], s[10:11], v0, s55, v[10:11]
	v_add_u32_e32 v0, s12, v0
	v_mad_i64_i32 v[14:15], s[10:11], v0, s35, v[12:13]
	v_add_u32_e32 v0, 0xd00, v189
	ds_read_b128 v[2:5], v2
	v_ashrrev_i32_e32 v0, 5, v0
	v_mad_u64_u32 v[6:7], s[10:11], v0, s55, v[10:11]
	ds_read_b128 v[6:9], v6
	v_add_u32_e32 v0, s12, v0
	s_waitcnt lgkmcnt(1)
	global_store_dwordx4 v[14:15], v[2:5], off nt
	s_nop 1
	v_mad_i64_i32 v[2:3], s[10:11], v0, s35, v[12:13]
	v_add_u32_e32 v0, 0xe00, v189
	v_ashrrev_i32_e32 v0, 5, v0
	s_waitcnt lgkmcnt(0)
	global_store_dwordx4 v[2:3], v[6:9], off nt
	v_mad_u64_u32 v[2:3], s[10:11], v0, s55, v[10:11]
	ds_read_b128 v[2:5], v2
	v_add_u32_e32 v0, s12, v0
	v_mad_i64_i32 v[14:15], s[10:11], v0, s35, v[12:13]
	v_add_u32_e32 v0, 0xf00, v189
	v_ashrrev_i32_e32 v0, 5, v0
	v_mad_u64_u32 v[6:7], s[10:11], v0, s55, v[10:11]
	ds_read_b128 v[6:9], v6
	v_add_u32_e32 v0, s12, v0
	s_waitcnt lgkmcnt(1)
	global_store_dwordx4 v[14:15], v[2:5], off nt
	s_nop 1
	v_mad_i64_i32 v[2:3], s[10:11], v0, s35, v[12:13]
	v_readlane_b32 s10, v252, 12
	s_add_i32 s22, s22, s10
	v_readlane_b32 s10, v252, 38
	s_cmp_ge_i32 s22, s10
	s_waitcnt lgkmcnt(0)
	global_store_dwordx4 v[2:3], v[6:9], off nt
	s_barrier
	s_cbranch_scc0 .LBB0_230

; #define LAS __attribute__((address_space(3)))
; DI f32x16 mfma32(bf16x8 a, bf16x8 b, f32x16 c) { return __builtin_amdgcn_mfma_f32_32x32x16_bf16(a, b, c, 0, 0, 0); }
;     ...
;   for (int kt = 0; kt < nk; ++kt) {
;     const int kn = (kt + 2 < nk) ? (kt + 2) : (nk - 1);
;     const LAS char* cur = lds + s0;
;     bf16x8 af[2][2], bfr[2][4];
; #pragma unroll
;     for (int kk = 0; kk < 2; ++kk) {
;       const int xo = kk ? x1 : x0;
;       af[kk][0] = *(const LAS bf16x8*)(cur + a_rd + xo);
;       bfr[kk][0] = *(const LAS bf16x8*)(cur + b_rd + xo);
;       bfr[kk][1] = *(const LAS bf16x8*)(cur + b_rd + 2048 + xo);
;       af[kk][1] = *(const LAS bf16x8*)(cur + a_rd + 2048 + xo);
;       bfr[kk][2] = *(const LAS bf16x8*)(cur + b_rd + 4096 + xo);
;       bfr[kk][3] = *(const LAS bf16x8*)(cur + b_rd + 6144 + xo);
;     }
;     DMA_STEP_(kn, s2);
; #pragma unroll
;     for (int kk = 0; kk < 2; ++kk) {
;       acc[0][0] = mfma32(bfr[kk][0], af[kk][0], acc[0][0]); acc[0][1] = mfma32(bfr[kk][1], af[kk][0], acc[0][1]);
;       acc[1][0] = mfma32(bfr[kk][0], af[kk][1], acc[1][0]); acc[1][1] = mfma32(bfr[kk][1], af[kk][1], acc[1][1]);
;       acc[0][2] = mfma32(bfr[kk][2], af[kk][0], acc[0][2]); acc[0][3] = mfma32(bfr[kk][3], af[kk][0], acc[0][3]);
;       acc[1][2] = mfma32(bfr[kk][2], af[kk][1], acc[1][2]); acc[1][3] = mfma32(bfr[kk][3], af[kk][1], acc[1][3]);
;     }
;     __builtin_amdgcn_sched_group_barrier(0x100, 12, 0);
;     __builtin_amdgcn_sched_group_barrier(0x010, 6, 0);
;     __builtin_amdgcn_sched_group_barrier(0x008, 16, 0);
;     asm volatile("s_waitcnt vmcnt(6) lgkmcnt(0)" ::: "memory");
;     __builtin_amdgcn_s_barrier();
;     asm volatile("" ::: "memory");
;     s0 = (s0 == 2 * STG) ? 0 : s0 + STG;
;     s2 = (s2 == 2 * STG) ? 0 : s2 + STG;
;   }
.LBB0_244:
	s_add_i32 s11, s46, 16
	s_add_i32 s10, s41, -1
	v_add_u32_e32 v142, s11, v219
	v_add_u32_e32 v150, s11, v218
	s_min_u32 s10, s10, 0x55
	v_add_u32_e32 v142, v142, v220
	v_add_u32_e32 v150, v150, v220
	s_lshl_b32 s70, s10, 6
	ds_read_b128 v[138:141], v142
	ds_read_b128 v[166:169], v150 offset:8192
	ds_read_b128 v[154:157], v150 offset:10240
	ds_read_b128 v[142:145], v142 offset:2048
	ds_read_b128 v[146:149], v150 offset:12288
	ds_read_b128 v[150:153], v150 offset:14336
	v_lshl_add_u64 v[222:223], v[192:193], 0, s[70:71]
	s_add_i32 s10, s44, s45
	v_lshl_add_u64 v[224:225], v[222:223], 0, s[24:25]
	s_mov_b32 m0, s10
	v_lshl_add_u64 v[222:223], v[222:223], 0, s[98:99]
	s_mul_i32 s100, s70, 0x400
	s_waitcnt lgkmcnt(6)
	v_mfma_f32_32x32x16_bf16 v[114:129], v[182:185], v[158:161], v[114:129]
	global_load_lds_dwordx4 v[224:225], off
	s_add_i32 m0, s10, 0x400
	v_mfma_f32_32x32x16_bf16 v[98:113], v[178:181], v[158:161], v[98:113]
	global_load_lds_dwordx4 v[222:223], off
	v_lshl_add_u64 v[224:225], v[194:195], 0, s[100:101]
	s_add_i32 s10, s43, s45
	s_add_i32 m0, s10, 0x2000
	v_mfma_f32_32x32x16_bf16 v[66:81], v[182:185], v[162:165], v[66:81]
	global_load_lds_dwordx4 v[224:225], off
	v_mfma_f32_32x32x16_bf16 v[34:49], v[178:181], v[162:165], v[34:49]
	global_load_lds_dwordx4 v[224:225], off offset:1024
	v_mfma_f32_32x32x16_bf16 v[82:97], v[174:177], v[158:161], v[82:97]
	global_load_lds_dwordx4 v[224:225], off offset:2048
	v_mfma_f32_32x32x16_bf16 v[50:65], v[170:173], v[158:161], v[50:65]
	global_load_lds_dwordx4 v[224:225], off offset:3072
	v_mfma_f32_32x32x16_bf16 v[18:33], v[174:177], v[162:165], v[18:33]
	s_add_i32 s10, s46, 0x6000
	s_cmpk_lg_u32 s46, 0xc000
	s_cselect_b32 s46, s10, 0
	s_add_i32 s10, s45, 0x6000
	s_cmpk_lg_u32 s45, 0xc000
	s_cselect_b32 s45, s10, 0
	v_mfma_f32_32x32x16_bf16 v[2:17], v[170:173], v[162:165], v[2:17]
	s_add_i32 s11, s46, 16
	s_waitcnt vmcnt(6) lgkmcnt(0)
	s_barrier
	v_add_u32_e32 v162, s11, v219
	v_add_u32_e32 v170, s11, v218
	v_add_u32_e32 v162, v162, v0
	v_add_u32_e32 v170, v170, v0
	ds_read_b128 v[158:161], v162
	ds_read_b128 v[182:185], v170 offset:8192
	ds_read_b128 v[178:181], v170 offset:10240
	ds_read_b128 v[162:165], v162 offset:2048
	ds_read_b128 v[174:177], v170 offset:12288
	ds_read_b128 v[170:173], v170 offset:14336
	v_mfma_f32_32x32x16_bf16 v[114:129], v[166:169], v[138:141], v[114:129]
	v_mfma_f32_32x32x16_bf16 v[98:113], v[154:157], v[138:141], v[98:113]
	v_mfma_f32_32x32x16_bf16 v[66:81], v[166:169], v[142:145], v[66:81]
	v_mfma_f32_32x32x16_bf16 v[34:49], v[154:157], v[142:145], v[34:49]
	v_mfma_f32_32x32x16_bf16 v[82:97], v[146:149], v[138:141], v[82:97]
	v_mfma_f32_32x32x16_bf16 v[50:65], v[150:153], v[138:141], v[50:65]
	v_mfma_f32_32x32x16_bf16 v[18:33], v[146:149], v[142:145], v[18:33]
	v_mfma_f32_32x32x16_bf16 v[2:17], v[150:153], v[142:145], v[2:17]
	s_add_i32 s11, s46, 16
	s_mov_b32 s10, s41
	v_add_u32_e32 v142, s11, v219
	v_add_u32_e32 v150, s11, v218
	s_min_u32 s10, s10, 0x55
	v_add_u32_e32 v142, v142, v220
	v_add_u32_e32 v150, v150, v220
	s_lshl_b32 s70, s10, 6
	ds_read_b128 v[138:141], v142
	ds_read_b128 v[166:169], v150 offset:8192
	ds_read_b128 v[154:157], v150 offset:10240
	ds_read_b128 v[142:145], v142 offset:2048
	ds_read_b128 v[146:149], v150 offset:12288
	ds_read_b128 v[150:153], v150 offset:14336
	v_lshl_add_u64 v[222:223], v[192:193], 0, s[70:71]
	s_add_i32 s10, s44, s45
	v_lshl_add_u64 v[224:225], v[222:223], 0, s[24:25]
	s_mov_b32 m0, s10
	v_lshl_add_u64 v[222:223], v[222:223], 0, s[98:99]
	s_mul_i32 s100, s70, 0x400
	s_waitcnt lgkmcnt(6)
	v_mfma_f32_32x32x16_bf16 v[114:129], v[182:185], v[158:161], v[114:129]
	global_load_lds_dwordx4 v[224:225], off
	s_add_i32 m0, s10, 0x400
	v_mfma_f32_32x32x16_bf16 v[98:113], v[178:181], v[158:161], v[98:113]
	global_load_lds_dwordx4 v[222:223], off
	v_lshl_add_u64 v[224:225], v[194:195], 0, s[100:101]
	s_add_i32 s10, s43, s45
	s_add_i32 m0, s10, 0x2000
	v_mfma_f32_32x32x16_bf16 v[66:81], v[182:185], v[162:165], v[66:81]
	global_load_lds_dwordx4 v[224:225], off
	v_mfma_f32_32x32x16_bf16 v[34:49], v[178:181], v[162:165], v[34:49]
	global_load_lds_dwordx4 v[224:225], off offset:1024
	v_mfma_f32_32x32x16_bf16 v[82:97], v[174:177], v[158:161], v[82:97]
	global_load_lds_dwordx4 v[224:225], off offset:2048
	v_mfma_f32_32x32x16_bf16 v[50:65], v[170:173], v[158:161], v[50:65]
	global_load_lds_dwordx4 v[224:225], off offset:3072
	v_mfma_f32_32x32x16_bf16 v[18:33], v[174:177], v[162:165], v[18:33]
	s_add_i32 s10, s46, 0x6000
	s_cmpk_lg_u32 s46, 0xc000
	s_cselect_b32 s46, s10, 0
	s_add_i32 s10, s45, 0x6000
	s_cmpk_lg_u32 s45, 0xc000
	s_cselect_b32 s45, s10, 0
	v_mfma_f32_32x32x16_bf16 v[2:17], v[170:173], v[162:165], v[2:17]
	s_add_i32 s11, s46, 16
	s_waitcnt vmcnt(6) lgkmcnt(0)
	s_barrier
	v_add_u32_e32 v162, s11, v219
	v_add_u32_e32 v170, s11, v218
	v_add_u32_e32 v162, v162, v0
	v_add_u32_e32 v170, v170, v0
	ds_read_b128 v[158:161], v162
	ds_read_b128 v[182:185], v170 offset:8192
	ds_read_b128 v[178:181], v170 offset:10240
	ds_read_b128 v[162:165], v162 offset:2048
	ds_read_b128 v[174:177], v170 offset:12288
	ds_read_b128 v[170:173], v170 offset:14336
	v_mfma_f32_32x32x16_bf16 v[114:129], v[166:169], v[138:141], v[114:129]
	v_mfma_f32_32x32x16_bf16 v[98:113], v[154:157], v[138:141], v[98:113]
	v_mfma_f32_32x32x16_bf16 v[66:81], v[166:169], v[142:145], v[66:81]
	v_mfma_f32_32x32x16_bf16 v[34:49], v[154:157], v[142:145], v[34:49]
	v_mfma_f32_32x32x16_bf16 v[82:97], v[146:149], v[138:141], v[82:97]
	v_mfma_f32_32x32x16_bf16 v[50:65], v[150:153], v[138:141], v[50:65]
	v_mfma_f32_32x32x16_bf16 v[18:33], v[146:149], v[142:145], v[18:33]
	v_mfma_f32_32x32x16_bf16 v[2:17], v[150:153], v[142:145], v[2:17]
	s_add_i32 s41, s41, 2
	s_cmpk_lg_i32 s41, 87
	s_cbranch_scc1 .LBB0_244
; #define LAS __attribute__((address_space(3)))
; DI unsigned pk2(float a, float b) { f32x2 v = {a, b}; bf2_t r = __builtin_convertvector(v, bf2_t); return __builtin_bit_cast(unsigned, r); }
; DI f32x16 mfma32(bf16x8 a, bf16x8 b, f32x16 c) { return __builtin_amdgcn_mfma_f32_32x32x16_bf16(a, b, c, 0, 0, 0); }
;     ...
;   for (int kt = 0; kt < nk; ++kt) {
;     const int kn = (kt + 2 < nk) ? (kt + 2) : (nk - 1);
;     const LAS char* cur = lds + s0;
;     bf16x8 af[2][2], bfr[2][4];
; #pragma unroll
;     for (int kk = 0; kk < 2; ++kk) {
;       const int xo = kk ? x1 : x0;
;       af[kk][0] = *(const LAS bf16x8*)(cur + a_rd + xo);
;       bfr[kk][0] = *(const LAS bf16x8*)(cur + b_rd + xo);
;       bfr[kk][1] = *(const LAS bf16x8*)(cur + b_rd + 2048 + xo);
;       af[kk][1] = *(const LAS bf16x8*)(cur + a_rd + 2048 + xo);
;       bfr[kk][2] = *(const LAS bf16x8*)(cur + b_rd + 4096 + xo);
;       bfr[kk][3] = *(const LAS bf16x8*)(cur + b_rd + 6144 + xo);
;     }
;     DMA_STEP_(kn, s2);
; #pragma unroll
;     for (int kk = 0; kk < 2; ++kk) {
;       acc[0][0] = mfma32(bfr[kk][0], af[kk][0], acc[0][0]); acc[0][1] = mfma32(bfr[kk][1], af[kk][0], acc[0][1]);
;       acc[1][0] = mfma32(bfr[kk][0], af[kk][1], acc[1][0]); acc[1][1] = mfma32(bfr[kk][1], af[kk][1], acc[1][1]);
;       acc[0][2] = mfma32(bfr[kk][2], af[kk][0], acc[0][2]); acc[0][3] = mfma32(bfr[kk][3], af[kk][0], acc[0][3]);
;       acc[1][2] = mfma32(bfr[kk][2], af[kk][1], acc[1][2]); acc[1][3] = mfma32(bfr[kk][3], af[kk][1], acc[1][3]);
;     }
;     __builtin_amdgcn_sched_group_barrier(0x100, 12, 0);
;     __builtin_amdgcn_sched_group_barrier(0x010, 6, 0);
;     __builtin_amdgcn_sched_group_barrier(0x008, 16, 0);
;     asm volatile("s_waitcnt vmcnt(6) lgkmcnt(0)" ::: "memory");
;     __builtin_amdgcn_s_barrier();
;     asm volatile("" ::: "memory");
;     s0 = (s0 == 2 * STG) ? 0 : s0 + STG;
;     s2 = (s2 == 2 * STG) ? 0 : s2 + STG;
;   }
;     ...
;   {
;     const int h = lane >> 5, cl = lane & 31;
; #pragma unroll
;     for (int i = 0; i < 2; ++i)
; #pragma unroll
;       for (int j = 0; j < 4; ++j)
; #pragma unroll
;         for (int g = 0; g < 4; ++g) {
;           u32x2 w; w.x = pk2(acc[i][j][4 * g], acc[i][j][4 * g + 1]); w.y = pk2(acc[i][j][4 * g + 2], acc[i][j][4 * g + 3]);
;           *(u32x2*)(smem + (wr * 64 + i * 32 + cl) * 528 + (wc * 128 + j * 32 + 8 * g + 4 * h) * 2) = w;
;         }
;   }
	s_add_i32 s11, s46, 16
	v_add_u32_e32 v142, s11, v219
	v_add_u32_e32 v150, s11, v218
	v_add_u32_e32 v142, v142, v220
	v_add_u32_e32 v150, v150, v220
	ds_read_b128 v[138:141], v142
	ds_read_b128 v[166:169], v150 offset:8192
	ds_read_b128 v[154:157], v150 offset:10240
	ds_read_b128 v[142:145], v142 offset:2048
	ds_read_b128 v[146:149], v150 offset:12288
	ds_read_b128 v[150:153], v150 offset:14336
	s_waitcnt lgkmcnt(6)
	v_mfma_f32_32x32x16_bf16 v[114:129], v[182:185], v[158:161], v[114:129]
	v_mfma_f32_32x32x16_bf16 v[98:113], v[178:181], v[158:161], v[98:113]
	v_mfma_f32_32x32x16_bf16 v[66:81], v[182:185], v[162:165], v[66:81]
	v_mfma_f32_32x32x16_bf16 v[34:49], v[178:181], v[162:165], v[34:49]
	v_mfma_f32_32x32x16_bf16 v[82:97], v[174:177], v[158:161], v[82:97]
	v_mfma_f32_32x32x16_bf16 v[50:65], v[170:173], v[158:161], v[50:65]
	v_mfma_f32_32x32x16_bf16 v[18:33], v[174:177], v[162:165], v[18:33]
	s_add_i32 s10, s46, 0x6000
	s_cmpk_lg_u32 s46, 0xc000
	s_cselect_b32 s46, s10, 0
	v_mfma_f32_32x32x16_bf16 v[2:17], v[170:173], v[162:165], v[2:17]
	s_add_i32 s11, s46, 16
	s_waitcnt vmcnt(0) lgkmcnt(0)
	s_barrier
	v_add_u32_e32 v162, s11, v219
	v_add_u32_e32 v170, s11, v218
	v_add_u32_e32 v162, v162, v0
	v_add_u32_e32 v170, v170, v0
	ds_read_b128 v[158:161], v162
	ds_read_b128 v[182:185], v170 offset:8192
	ds_read_b128 v[178:181], v170 offset:10240
	ds_read_b128 v[162:165], v162 offset:2048
	ds_read_b128 v[174:177], v170 offset:12288
	ds_read_b128 v[170:173], v170 offset:14336
	v_mfma_f32_32x32x16_bf16 v[114:129], v[166:169], v[138:141], v[114:129]
	v_mfma_f32_32x32x16_bf16 v[98:113], v[154:157], v[138:141], v[98:113]
	v_mfma_f32_32x32x16_bf16 v[66:81], v[166:169], v[142:145], v[66:81]
	v_mfma_f32_32x32x16_bf16 v[34:49], v[154:157], v[142:145], v[34:49]
	v_mfma_f32_32x32x16_bf16 v[82:97], v[146:149], v[138:141], v[82:97]
	v_mfma_f32_32x32x16_bf16 v[50:65], v[150:153], v[138:141], v[50:65]
	v_mfma_f32_32x32x16_bf16 v[18:33], v[146:149], v[142:145], v[18:33]
	v_mfma_f32_32x32x16_bf16 v[2:17], v[150:153], v[142:145], v[2:17]
	s_add_i32 s11, s46, 16
	v_add_u32_e32 v142, s11, v219
	v_add_u32_e32 v150, s11, v218
	v_add_u32_e32 v142, v142, v220
	v_add_u32_e32 v150, v150, v220
	ds_read_b128 v[138:141], v142
	ds_read_b128 v[166:169], v150 offset:8192
	ds_read_b128 v[154:157], v150 offset:10240
	ds_read_b128 v[142:145], v142 offset:2048
	ds_read_b128 v[146:149], v150 offset:12288
	ds_read_b128 v[150:153], v150 offset:14336
	s_waitcnt lgkmcnt(6)
	v_mfma_f32_32x32x16_bf16 v[114:129], v[182:185], v[158:161], v[114:129]
	v_mfma_f32_32x32x16_bf16 v[98:113], v[178:181], v[158:161], v[98:113]
	v_mfma_f32_32x32x16_bf16 v[66:81], v[182:185], v[162:165], v[66:81]
	v_mfma_f32_32x32x16_bf16 v[34:49], v[178:181], v[162:165], v[34:49]
	v_mfma_f32_32x32x16_bf16 v[82:97], v[174:177], v[158:161], v[82:97]
	v_mfma_f32_32x32x16_bf16 v[50:65], v[170:173], v[158:161], v[50:65]
	v_mfma_f32_32x32x16_bf16 v[18:33], v[174:177], v[162:165], v[18:33]
	v_mfma_f32_32x32x16_bf16 v[2:17], v[170:173], v[162:165], v[2:17]
	s_waitcnt lgkmcnt(0)
	v_mfma_f32_32x32x16_bf16 v[114:129], v[166:169], v[138:141], v[114:129]
	v_mfma_f32_32x32x16_bf16 v[98:113], v[154:157], v[138:141], v[98:113]
	v_mfma_f32_32x32x16_bf16 v[66:81], v[166:169], v[142:145], v[66:81]
	v_mfma_f32_32x32x16_bf16 v[34:49], v[154:157], v[142:145], v[34:49]
	v_mfma_f32_32x32x16_bf16 v[82:97], v[146:149], v[138:141], v[82:97]
	v_mfma_f32_32x32x16_bf16 v[50:65], v[150:153], v[138:141], v[50:65]
	v_mfma_f32_32x32x16_bf16 v[18:33], v[146:149], v[142:145], v[18:33]
	v_mfma_f32_32x32x16_bf16 v[2:17], v[150:153], v[142:145], v[2:17]
	s_waitcnt lgkmcnt(0)
	s_setprio 0
	v_mul_lo_u32 v0, v197, s55
	v_add_u32_e32 v0, 16, v0
	s_nop 1
	v_cvt_pk_bf16_f32 v114, v114, v115
	v_cvt_pk_bf16_f32 v115, v116, v117
	v_lshlrev_b32_e32 v116, 3, v196
	s_lshl_b32 s10, s42, 1
	v_add3_u32 v0, v0, v116, s10
	v_cvt_pk_bf16_f32 v116, v118, v119
	v_cvt_pk_bf16_f32 v117, v120, v121
	v_cvt_pk_bf16_f32 v98, v98, v99
	v_cvt_pk_bf16_f32 v99, v100, v101
	v_cvt_pk_bf16_f32 v100, v102, v103
	v_cvt_pk_bf16_f32 v101, v104, v105
	v_cvt_pk_bf16_f32 v82, v82, v83
	v_cvt_pk_bf16_f32 v83, v84, v85
	v_cvt_pk_bf16_f32 v84, v86, v87
	v_cvt_pk_bf16_f32 v85, v88, v89
	v_cvt_pk_bf16_f32 v50, v50, v51
	v_cvt_pk_bf16_f32 v51, v52, v53
	v_cvt_pk_bf16_f32 v52, v54, v55
	v_cvt_pk_bf16_f32 v53, v56, v57
	s_waitcnt vmcnt(0)
	s_barrier
; DI unsigned pk2(float a, float b) { f32x2 v = {a, b}; bf2_t r = __builtin_convertvector(v, bf2_t); return __builtin_bit_cast(unsigned, r); }
;     ...
;   {
;     const int h = lane >> 5, cl = lane & 31;
; #pragma unroll
;     for (int i = 0; i < 2; ++i)
; #pragma unroll
;       for (int j = 0; j < 4; ++j)
; #pragma unroll
;         for (int g = 0; g < 4; ++g) {
;           u32x2 w; w.x = pk2(acc[i][j][4 * g], acc[i][j][4 * g + 1]); w.y = pk2(acc[i][j][4 * g + 2], acc[i][j][4 * g + 3]);
;           *(u32x2*)(smem + (wr * 64 + i * 32 + cl) * 528 + (wc * 128 + j * 32 + 8 * g + 4 * h) * 2) = w;
;         }
;   }
;   __syncthreads();
	ds_write2_b64 v0, v[114:115], v[116:117] offset1:2
	v_cvt_pk_bf16_f32 v114, v122, v123
	v_cvt_pk_bf16_f32 v115, v124, v125
	v_cvt_pk_bf16_f32 v116, v126, v127
	v_cvt_pk_bf16_f32 v117, v128, v129
	ds_write2_b64 v0, v[98:99], v[100:101] offset0:8 offset1:10
	v_cvt_pk_bf16_f32 v98, v106, v107
	v_cvt_pk_bf16_f32 v99, v108, v109
	v_cvt_pk_bf16_f32 v100, v110, v111
	v_cvt_pk_bf16_f32 v101, v112, v113
	ds_write2_b64 v0, v[82:83], v[84:85] offset0:16 offset1:18
	v_cvt_pk_bf16_f32 v82, v90, v91
	v_cvt_pk_bf16_f32 v83, v92, v93
	v_cvt_pk_bf16_f32 v84, v94, v95
	v_cvt_pk_bf16_f32 v85, v96, v97
	ds_write2_b64 v0, v[50:51], v[52:53] offset0:24 offset1:26
	v_cvt_pk_bf16_f32 v50, v58, v59
	v_cvt_pk_bf16_f32 v51, v60, v61
	v_cvt_pk_bf16_f32 v52, v62, v63
	v_cvt_pk_bf16_f32 v53, v64, v65
	ds_write2_b64 v0, v[114:115], v[116:117] offset0:4 offset1:6
	ds_write2_b64 v0, v[98:99], v[100:101] offset0:12 offset1:14
	ds_write2_b64 v0, v[82:83], v[84:85] offset0:20 offset1:22
	ds_write2_b64 v0, v[50:51], v[52:53] offset0:28 offset1:30
	v_cvt_pk_bf16_f32 v50, v66, v67
	v_cvt_pk_bf16_f32 v51, v68, v69
	v_cvt_pk_bf16_f32 v52, v70, v71
	v_cvt_pk_bf16_f32 v53, v72, v73
	v_add_u32_e32 v0, 0x4000, v0
	v_cvt_pk_bf16_f32 v34, v34, v35
	v_cvt_pk_bf16_f32 v35, v36, v37
	v_cvt_pk_bf16_f32 v36, v38, v39
	v_cvt_pk_bf16_f32 v37, v40, v41
	v_cvt_pk_bf16_f32 v18, v18, v19
	v_cvt_pk_bf16_f32 v19, v20, v21
	v_cvt_pk_bf16_f32 v20, v22, v23
	v_cvt_pk_bf16_f32 v21, v24, v25
	v_cvt_pk_bf16_f32 v2, v2, v3
	v_cvt_pk_bf16_f32 v3, v4, v5
	v_cvt_pk_bf16_f32 v4, v6, v7
	v_cvt_pk_bf16_f32 v5, v8, v9
	ds_write2_b64 v0, v[50:51], v[52:53] offset0:64 offset1:66
	v_cvt_pk_bf16_f32 v50, v74, v75
	v_cvt_pk_bf16_f32 v51, v76, v77
	v_cvt_pk_bf16_f32 v52, v78, v79
	v_cvt_pk_bf16_f32 v53, v80, v81
	ds_write2_b64 v0, v[34:35], v[36:37] offset0:72 offset1:74
	v_cvt_pk_bf16_f32 v34, v42, v43
	v_cvt_pk_bf16_f32 v35, v44, v45
	v_cvt_pk_bf16_f32 v36, v46, v47
	v_cvt_pk_bf16_f32 v37, v48, v49
	ds_write2_b64 v0, v[18:19], v[20:21] offset0:80 offset1:82
	v_cvt_pk_bf16_f32 v18, v26, v27
	v_cvt_pk_bf16_f32 v19, v28, v29
	v_cvt_pk_bf16_f32 v20, v30, v31
	v_cvt_pk_bf16_f32 v21, v32, v33
	ds_write2_b64 v0, v[2:3], v[4:5] offset0:88 offset1:90
	v_cvt_pk_bf16_f32 v2, v10, v11
	v_cvt_pk_bf16_f32 v3, v12, v13
	v_cvt_pk_bf16_f32 v4, v14, v15
	v_cvt_pk_bf16_f32 v5, v16, v17
	s_lshl_b64 s[10:11], s[16:17], 1
	ds_write2_b64 v0, v[50:51], v[52:53] offset0:68 offset1:70
	ds_write2_b64 v0, v[34:35], v[36:37] offset0:76 offset1:78
	ds_write2_b64 v0, v[18:19], v[20:21] offset0:84 offset1:86
	ds_write2_b64 v0, v[2:3], v[4:5] offset0:92 offset1:94
	s_waitcnt vmcnt(0) lgkmcnt(0)
	s_barrier
; #define GAS __attribute__((address_space(1)))
;     ...
;   if (EPI == 0) {
; #pragma unroll
;     for (int i = 0; i < 16; ++i) {
;       const int id = tid2 + 256 * i, r = id >> 5, c8 = (id & 31) * 8;
;       const u32x4 v = *(const u32x4*)(smem + r * 528 + c8 * 2);
;       *(GAS u32x4*)(ea.out + (size_t)(m0 + r) * ea.ldo + n0 + c8) = v;
;     }
	s_add_u32 s10, s21, s10
	v_lshlrev_b32_e32 v0, 4, v189
	v_and_b32_e32 v0, 0x1f0, v0
	s_addc_u32 s11, s22, s11
	v_add_u32_e32 v10, 16, v0
	v_lshl_add_u64 v[12:13], s[10:11], 0, v[0:1]
	v_ashrrev_i32_e32 v0, 5, v189
	v_mad_u64_u32 v[2:3], s[10:11], v0, s55, v[10:11]
	ds_read_b128 v[2:5], v2
	v_add_u32_e32 v6, s40, v0
	v_ashrrev_i32_e32 v7, 31, v6
	v_add_u32_e32 v0, 0x100, v189
	v_lshlrev_b64 v[6:7], 11, v[6:7]
	v_ashrrev_i32_e32 v0, 5, v0
	v_lshl_add_u64 v[14:15], v[12:13], 0, v[6:7]
	v_mad_u64_u32 v[6:7], s[10:11], v0, s55, v[10:11]
	ds_read_b128 v[6:9], v6
	s_waitcnt lgkmcnt(1)
	global_store_dwordx4 v[14:15], v[2:5], off nt
	s_nop 1
	v_add_u32_e32 v2, s40, v0
	v_ashrrev_i32_e32 v3, 31, v2
	v_lshlrev_b64 v[2:3], 11, v[2:3]
	v_add_u32_e32 v0, 0x200, v189
	v_lshl_add_u64 v[2:3], v[12:13], 0, v[2:3]
	v_ashrrev_i32_e32 v0, 5, v0
	s_waitcnt lgkmcnt(0)
	global_store_dwordx4 v[2:3], v[6:9], off nt
	v_mad_u64_u32 v[2:3], s[10:11], v0, s55, v[10:11]
	ds_read_b128 v[2:5], v2
	v_add_u32_e32 v6, s40, v0
	v_ashrrev_i32_e32 v7, 31, v6
	v_add_u32_e32 v0, 0x300, v189
	v_lshlrev_b64 v[6:7], 11, v[6:7]
	v_ashrrev_i32_e32 v0, 5, v0
	v_lshl_add_u64 v[14:15], v[12:13], 0, v[6:7]
	v_mad_u64_u32 v[6:7], s[10:11], v0, s55, v[10:11]
	ds_read_b128 v[6:9], v6
	s_waitcnt lgkmcnt(1)
	global_store_dwordx4 v[14:15], v[2:5], off nt
	s_nop 1
	v_add_u32_e32 v2, s40, v0
	v_ashrrev_i32_e32 v3, 31, v2
	v_lshlrev_b64 v[2:3], 11, v[2:3]
	v_add_u32_e32 v0, 0x400, v189
	v_lshl_add_u64 v[2:3], v[12:13], 0, v[2:3]
	v_ashrrev_i32_e32 v0, 5, v0
	s_waitcnt lgkmcnt(0)
	global_store_dwordx4 v[2:3], v[6:9], off nt
	v_mad_u64_u32 v[2:3], s[10:11], v0, s55, v[10:11]
	ds_read_b128 v[2:5], v2
	v_add_u32_e32 v6, s40, v0
	v_ashrrev_i32_e32 v7, 31, v6
	v_add_u32_e32 v0, 0x500, v189
	v_lshlrev_b64 v[6:7], 11, v[6:7]
	v_ashrrev_i32_e32 v0, 5, v0
	v_lshl_add_u64 v[14:15], v[12:13], 0, v[6:7]
	v_mad_u64_u32 v[6:7], s[10:11], v0, s55, v[10:11]
	ds_read_b128 v[6:9], v6
	s_waitcnt lgkmcnt(1)
	global_store_dwordx4 v[14:15], v[2:5], off nt
	s_nop 1
	v_add_u32_e32 v2, s40, v0
	v_ashrrev_i32_e32 v3, 31, v2
	v_lshlrev_b64 v[2:3], 11, v[2:3]
	v_add_u32_e32 v0, 0x600, v189
	v_lshl_add_u64 v[2:3], v[12:13], 0, v[2:3]
	v_ashrrev_i32_e32 v0, 5, v0
	s_waitcnt lgkmcnt(0)
	global_store_dwordx4 v[2:3], v[6:9], off nt
	v_mad_u64_u32 v[2:3], s[10:11], v0, s55, v[10:11]
	ds_read_b128 v[2:5], v2
	v_add_u32_e32 v6, s40, v0
	v_ashrrev_i32_e32 v7, 31, v6
	v_add_u32_e32 v0, 0x700, v189
	v_lshlrev_b64 v[6:7], 11, v[6:7]
	v_ashrrev_i32_e32 v0, 5, v0
	v_lshl_add_u64 v[14:15], v[12:13], 0, v[6:7]
	v_mad_u64_u32 v[6:7], s[10:11], v0, s55, v[10:11]
	ds_read_b128 v[6:9], v6
	s_waitcnt lgkmcnt(1)
	global_store_dwordx4 v[14:15], v[2:5], off nt
	s_nop 1
	v_add_u32_e32 v2, s40, v0
	v_ashrrev_i32_e32 v3, 31, v2
	v_lshlrev_b64 v[2:3], 11, v[2:3]
	v_add_u32_e32 v0, 0x800, v189
	v_lshl_add_u64 v[2:3], v[12:13], 0, v[2:3]
	v_ashrrev_i32_e32 v0, 5, v0
	s_waitcnt lgkmcnt(0)
	global_store_dwordx4 v[2:3], v[6:9], off nt
	v_mad_u64_u32 v[2:3], s[10:11], v0, s55, v[10:11]
	ds_read_b128 v[2:5], v2
	v_add_u32_e32 v6, s40, v0
	v_ashrrev_i32_e32 v7, 31, v6
	v_add_u32_e32 v0, 0x900, v189
	v_lshlrev_b64 v[6:7], 11, v[6:7]
	v_ashrrev_i32_e32 v0, 5, v0
	v_lshl_add_u64 v[14:15], v[12:13], 0, v[6:7]
	v_mad_u64_u32 v[6:7], s[10:11], v0, s55, v[10:11]
	ds_read_b128 v[6:9], v6
	s_waitcnt lgkmcnt(1)
	global_store_dwordx4 v[14:15], v[2:5], off nt
	s_nop 1
	v_add_u32_e32 v2, s40, v0
	v_ashrrev_i32_e32 v3, 31, v2
	v_lshlrev_b64 v[2:3], 11, v[2:3]
	v_add_u32_e32 v0, 0xa00, v189
	v_lshl_add_u64 v[2:3], v[12:13], 0, v[2:3]
	v_ashrrev_i32_e32 v0, 5, v0
	s_waitcnt lgkmcnt(0)
	global_store_dwordx4 v[2:3], v[6:9], off nt
	v_mad_u64_u32 v[2:3], s[10:11], v0, s55, v[10:11]
	ds_read_b128 v[2:5], v2
	v_add_u32_e32 v6, s40, v0
	v_ashrrev_i32_e32 v7, 31, v6
	v_add_u32_e32 v0, 0xb00, v189
	v_lshlrev_b64 v[6:7], 11, v[6:7]
	v_ashrrev_i32_e32 v0, 5, v0
	v_lshl_add_u64 v[14:15], v[12:13], 0, v[6:7]
	v_mad_u64_u32 v[6:7], s[10:11], v0, s55, v[10:11]
	ds_read_b128 v[6:9], v6
	s_waitcnt lgkmcnt(1)
	global_store_dwordx4 v[14:15], v[2:5], off nt
	s_nop 1
	v_add_u32_e32 v2, s40, v0
	v_ashrrev_i32_e32 v3, 31, v2
	v_lshlrev_b64 v[2:3], 11, v[2:3]
	v_add_u32_e32 v0, 0xc00, v189
	v_lshl_add_u64 v[2:3], v[12:13], 0, v[2:3]
	v_ashrrev_i32_e32 v0, 5, v0
	s_waitcnt lgkmcnt(0)
	global_store_dwordx4 v[2:3], v[6:9], off nt
	v_mad_u64_u32 v[2:3], s[10:11], v0, s55, v[10:11]
	ds_read_b128 v[2:5], v2
	v_add_u32_e32 v6, s40, v0
	v_ashrrev_i32_e32 v7, 31, v6
	v_add_u32_e32 v0, 0xd00, v189
	v_lshlrev_b64 v[6:7], 11, v[6:7]
	v_ashrrev_i32_e32 v0, 5, v0
	v_lshl_add_u64 v[14:15], v[12:13], 0, v[6:7]
	v_mad_u64_u32 v[6:7], s[10:11], v0, s55, v[10:11]
	ds_read_b128 v[6:9], v6
	s_waitcnt lgkmcnt(1)
	global_store_dwordx4 v[14:15], v[2:5], off nt
	s_nop 1
	v_add_u32_e32 v2, s40, v0
	v_ashrrev_i32_e32 v3, 31, v2
	v_lshlrev_b64 v[2:3], 11, v[2:3]
	v_add_u32_e32 v0, 0xe00, v189
	v_lshl_add_u64 v[2:3], v[12:13], 0, v[2:3]
	v_ashrrev_i32_e32 v0, 5, v0
	s_waitcnt lgkmcnt(0)
	global_store_dwordx4 v[2:3], v[6:9], off nt
	v_mad_u64_u32 v[2:3], s[10:11], v0, s55, v[10:11]
	ds_read_b128 v[2:5], v2
	v_add_u32_e32 v6, s40, v0
	v_ashrrev_i32_e32 v7, 31, v6
	v_add_u32_e32 v0, 0xf00, v189
	v_lshlrev_b64 v[6:7], 11, v[6:7]
	v_ashrrev_i32_e32 v0, 5, v0
	v_lshl_add_u64 v[14:15], v[12:13], 0, v[6:7]
	v_mad_u64_u32 v[6:7], s[10:11], v0, s55, v[10:11]
	ds_read_b128 v[6:9], v6
	s_waitcnt lgkmcnt(1)
	global_store_dwordx4 v[14:15], v[2:5], off nt
	v_readlane_b32 s10, v252, 12
	s_add_i32 s29, s29, s10
	v_add_u32_e32 v2, s40, v0
	v_ashrrev_i32_e32 v3, 31, v2
	v_lshlrev_b64 v[2:3], 11, v[2:3]
	v_lshl_add_u64 v[2:3], v[12:13], 0, v[2:3]
	s_cmp_ge_i32 s29, s18
	s_waitcnt lgkmcnt(0)
	global_store_dwordx4 v[2:3], v[6:9], off nt
	s_barrier
	s_cbranch_scc0 .LBB0_243

; #define LAS __attribute__((address_space(3)))
; DI f32x16 mfma32(bf16x8 a, bf16x8 b, f32x16 c) { return __builtin_amdgcn_mfma_f32_32x32x16_bf16(a, b, c, 0, 0, 0); }
;     ...
;   for (int kt = 0; kt < nk; ++kt) {
;     const int kn = (kt + 2 < nk) ? (kt + 2) : (nk - 1);
;     const LAS char* cur = lds + s0;
;     bf16x8 af[2][2], bfr[2][4];
; #pragma unroll
;     for (int kk = 0; kk < 2; ++kk) {
;       const int xo = kk ? x1 : x0;
;       af[kk][0] = *(const LAS bf16x8*)(cur + a_rd + xo);
;       bfr[kk][0] = *(const LAS bf16x8*)(cur + b_rd + xo);
;       bfr[kk][1] = *(const LAS bf16x8*)(cur + b_rd + 2048 + xo);
;       af[kk][1] = *(const LAS bf16x8*)(cur + a_rd + 2048 + xo);
;       bfr[kk][2] = *(const LAS bf16x8*)(cur + b_rd + 4096 + xo);
;       bfr[kk][3] = *(const LAS bf16x8*)(cur + b_rd + 6144 + xo);
;     }
;     DMA_STEP_(kn, s2);
; #pragma unroll
;     for (int kk = 0; kk < 2; ++kk) {
;       acc[0][0] = mfma32(bfr[kk][0], af[kk][0], acc[0][0]); acc[0][1] = mfma32(bfr[kk][1], af[kk][0], acc[0][1]);
;       acc[1][0] = mfma32(bfr[kk][0], af[kk][1], acc[1][0]); acc[1][1] = mfma32(bfr[kk][1], af[kk][1], acc[1][1]);
;       acc[0][2] = mfma32(bfr[kk][2], af[kk][0], acc[0][2]); acc[0][3] = mfma32(bfr[kk][3], af[kk][0], acc[0][3]);
;       acc[1][2] = mfma32(bfr[kk][2], af[kk][1], acc[1][2]); acc[1][3] = mfma32(bfr[kk][3], af[kk][1], acc[1][3]);
;     }
;     __builtin_amdgcn_sched_group_barrier(0x100, 12, 0);
;     __builtin_amdgcn_sched_group_barrier(0x010, 6, 0);
;     __builtin_amdgcn_sched_group_barrier(0x008, 16, 0);
;     asm volatile("s_waitcnt vmcnt(6) lgkmcnt(0)" ::: "memory");
;     __builtin_amdgcn_s_barrier();
;     asm volatile("" ::: "memory");
;     s0 = (s0 == 2 * STG) ? 0 : s0 + STG;
;     s2 = (s2 == 2 * STG) ? 0 : s2 + STG;
;   }
.LBB0_272:
	s_add_i32 s11, s28, 16
	s_mov_b32 s10, s21
	v_add_u32_e32 v142, s11, v218
	v_add_u32_e32 v150, s11, v0
	s_min_u32 s10, s10, 29
	v_add_u32_e32 v142, v142, v220
	v_add_u32_e32 v150, v150, v220
	s_lshl_b32 s70, s10, 6
	ds_read_b128 v[138:141], v142
	ds_read_b128 v[162:165], v150 offset:8192
	ds_read_b128 v[166:169], v150 offset:10240
	ds_read_b128 v[142:145], v142 offset:2048
	ds_read_b128 v[146:149], v150 offset:12288
	ds_read_b128 v[150:153], v150 offset:14336
	s_mul_i32 vcc_lo, s70, 0x12000
	s_add_i32 s10, s20, s23
	v_lshl_add_u64 v[222:223], v[192:193], 0, vcc
	s_mov_b32 m0, s10
	s_mul_i32 s100, s70, 0x1600
	v_lshl_add_u64 v[224:225], v[194:195], 0, s[100:101]
	s_add_i32 s10, s19, s23
	s_waitcnt lgkmcnt(6)
	v_mfma_f32_32x32x16_bf16 v[66:81], v[182:185], v[154:157], v[66:81]
	global_load_lds_dwordx4 v[222:223], off
	v_mfma_f32_32x32x16_bf16 v[82:97], v[178:181], v[154:157], v[82:97]
	global_load_lds_dwordx4 v[222:223], off offset:1024
	s_add_i32 m0, s10, 0x2000
	v_mfma_f32_32x32x16_bf16 v[18:33], v[182:185], v[158:161], v[18:33]
	global_load_lds_dwordx4 v[224:225], off
	v_mfma_f32_32x32x16_bf16 v[2:17], v[178:181], v[158:161], v[2:17]
	global_load_lds_dwordx4 v[224:225], off offset:1024
	v_mfma_f32_32x32x16_bf16 v[114:129], v[174:177], v[154:157], v[114:129]
	global_load_lds_dwordx4 v[224:225], off offset:2048
	v_mfma_f32_32x32x16_bf16 v[98:113], v[170:173], v[154:157], v[98:113]
	global_load_lds_dwordx4 v[224:225], off offset:3072
	v_mfma_f32_32x32x16_bf16 v[50:65], v[174:177], v[158:161], v[50:65]
	s_add_i32 s10, s28, 0x6000
	s_cmpk_lg_u32 s28, 0xc000
	s_cselect_b32 s28, s10, 0
	s_add_i32 s10, s23, 0x6000
	s_cmpk_lg_u32 s23, 0xc000
	s_cselect_b32 s23, s10, 0
	v_mfma_f32_32x32x16_bf16 v[34:49], v[170:173], v[158:161], v[34:49]
	s_add_i32 s11, s28, 16
	s_waitcnt vmcnt(6) lgkmcnt(0)
	s_barrier
	v_add_u32_e32 v158, s11, v218
	v_add_u32_e32 v170, s11, v0
	v_add_u32_e32 v158, v158, v219
	v_add_u32_e32 v170, v170, v219
	ds_read_b128 v[154:157], v158
	ds_read_b128 v[182:185], v170 offset:8192
	ds_read_b128 v[178:181], v170 offset:10240
	ds_read_b128 v[158:161], v158 offset:2048
	ds_read_b128 v[174:177], v170 offset:12288
	ds_read_b128 v[170:173], v170 offset:14336
	v_mfma_f32_32x32x16_bf16 v[66:81], v[162:165], v[138:141], v[66:81]
	v_mfma_f32_32x32x16_bf16 v[82:97], v[166:169], v[138:141], v[82:97]
	v_mfma_f32_32x32x16_bf16 v[18:33], v[162:165], v[142:145], v[18:33]
	v_mfma_f32_32x32x16_bf16 v[2:17], v[166:169], v[142:145], v[2:17]
	v_mfma_f32_32x32x16_bf16 v[114:129], v[146:149], v[138:141], v[114:129]
	v_mfma_f32_32x32x16_bf16 v[98:113], v[150:153], v[138:141], v[98:113]
	v_mfma_f32_32x32x16_bf16 v[50:65], v[146:149], v[142:145], v[50:65]
	v_mfma_f32_32x32x16_bf16 v[34:49], v[150:153], v[142:145], v[34:49]
	s_add_i32 s11, s28, 16
	s_add_i32 s10, s21, 1
	v_add_u32_e32 v142, s11, v218
	v_add_u32_e32 v150, s11, v0
	s_min_u32 s10, s10, 29
	v_add_u32_e32 v142, v142, v220
	v_add_u32_e32 v150, v150, v220
	s_lshl_b32 s70, s10, 6
	ds_read_b128 v[138:141], v142
	ds_read_b128 v[162:165], v150 offset:8192
	ds_read_b128 v[166:169], v150 offset:10240
	ds_read_b128 v[142:145], v142 offset:2048
	ds_read_b128 v[146:149], v150 offset:12288
	ds_read_b128 v[150:153], v150 offset:14336
	s_mul_i32 vcc_lo, s70, 0x12000
	s_add_i32 s10, s20, s23
	v_lshl_add_u64 v[222:223], v[192:193], 0, vcc
	s_mov_b32 m0, s10
	s_mul_i32 s100, s70, 0x1600
	v_lshl_add_u64 v[224:225], v[194:195], 0, s[100:101]
	s_add_i32 s10, s19, s23
	s_waitcnt lgkmcnt(6)
	v_mfma_f32_32x32x16_bf16 v[66:81], v[182:185], v[154:157], v[66:81]
	global_load_lds_dwordx4 v[222:223], off
	v_mfma_f32_32x32x16_bf16 v[82:97], v[178:181], v[154:157], v[82:97]
	global_load_lds_dwordx4 v[222:223], off offset:1024
	s_add_i32 m0, s10, 0x2000
	v_mfma_f32_32x32x16_bf16 v[18:33], v[182:185], v[158:161], v[18:33]
	global_load_lds_dwordx4 v[224:225], off
	v_mfma_f32_32x32x16_bf16 v[2:17], v[178:181], v[158:161], v[2:17]
	global_load_lds_dwordx4 v[224:225], off offset:1024
	v_mfma_f32_32x32x16_bf16 v[114:129], v[174:177], v[154:157], v[114:129]
	global_load_lds_dwordx4 v[224:225], off offset:2048
	v_mfma_f32_32x32x16_bf16 v[98:113], v[170:173], v[154:157], v[98:113]
	global_load_lds_dwordx4 v[224:225], off offset:3072
	v_mfma_f32_32x32x16_bf16 v[50:65], v[174:177], v[158:161], v[50:65]
	s_add_i32 s10, s28, 0x6000
	s_cmpk_lg_u32 s28, 0xc000
	s_cselect_b32 s28, s10, 0
	s_add_i32 s10, s23, 0x6000
	s_cmpk_lg_u32 s23, 0xc000
	s_cselect_b32 s23, s10, 0
	v_mfma_f32_32x32x16_bf16 v[34:49], v[170:173], v[158:161], v[34:49]
	s_add_i32 s11, s28, 16
	s_waitcnt vmcnt(6) lgkmcnt(0)
	s_barrier
	v_add_u32_e32 v158, s11, v218
	v_add_u32_e32 v170, s11, v0
	v_add_u32_e32 v158, v158, v219
	v_add_u32_e32 v170, v170, v219
	ds_read_b128 v[154:157], v158
	ds_read_b128 v[182:185], v170 offset:8192
	ds_read_b128 v[178:181], v170 offset:10240
	ds_read_b128 v[158:161], v158 offset:2048
	ds_read_b128 v[174:177], v170 offset:12288
	ds_read_b128 v[170:173], v170 offset:14336
	v_mfma_f32_32x32x16_bf16 v[66:81], v[162:165], v[138:141], v[66:81]
	v_mfma_f32_32x32x16_bf16 v[82:97], v[166:169], v[138:141], v[82:97]
	v_mfma_f32_32x32x16_bf16 v[18:33], v[162:165], v[142:145], v[18:33]
	v_mfma_f32_32x32x16_bf16 v[2:17], v[166:169], v[142:145], v[2:17]
	v_mfma_f32_32x32x16_bf16 v[114:129], v[146:149], v[138:141], v[114:129]
	v_mfma_f32_32x32x16_bf16 v[98:113], v[150:153], v[138:141], v[98:113]
	v_mfma_f32_32x32x16_bf16 v[50:65], v[146:149], v[142:145], v[50:65]
	v_mfma_f32_32x32x16_bf16 v[34:49], v[150:153], v[142:145], v[34:49]
	s_add_i32 s21, s21, 2
	s_cmp_eq_u32 s21, 30
	s_cbranch_scc0 .LBB0_272
; #define LAS __attribute__((address_space(3)))
; DI f32x16 mfma32(bf16x8 a, bf16x8 b, f32x16 c) { return __builtin_amdgcn_mfma_f32_32x32x16_bf16(a, b, c, 0, 0, 0); }
;     ...
;   for (int kt = 0; kt < nk; ++kt) {
;     const int kn = (kt + 2 < nk) ? (kt + 2) : (nk - 1);
;     const LAS char* cur = lds + s0;
;     bf16x8 af[2][2], bfr[2][4];
; #pragma unroll
;     for (int kk = 0; kk < 2; ++kk) {
;       const int xo = kk ? x1 : x0;
;       af[kk][0] = *(const LAS bf16x8*)(cur + a_rd + xo);
;       bfr[kk][0] = *(const LAS bf16x8*)(cur + b_rd + xo);
;       bfr[kk][1] = *(const LAS bf16x8*)(cur + b_rd + 2048 + xo);
;       af[kk][1] = *(const LAS bf16x8*)(cur + a_rd + 2048 + xo);
;       bfr[kk][2] = *(const LAS bf16x8*)(cur + b_rd + 4096 + xo);
;       bfr[kk][3] = *(const LAS bf16x8*)(cur + b_rd + 6144 + xo);
;     }
;     DMA_STEP_(kn, s2);
; #pragma unroll
;     for (int kk = 0; kk < 2; ++kk) {
;       acc[0][0] = mfma32(bfr[kk][0], af[kk][0], acc[0][0]); acc[0][1] = mfma32(bfr[kk][1], af[kk][0], acc[0][1]);
;       acc[1][0] = mfma32(bfr[kk][0], af[kk][1], acc[1][0]); acc[1][1] = mfma32(bfr[kk][1], af[kk][1], acc[1][1]);
;       acc[0][2] = mfma32(bfr[kk][2], af[kk][0], acc[0][2]); acc[0][3] = mfma32(bfr[kk][3], af[kk][0], acc[0][3]);
;       acc[1][2] = mfma32(bfr[kk][2], af[kk][1], acc[1][2]); acc[1][3] = mfma32(bfr[kk][3], af[kk][1], acc[1][3]);
;     }
;     __builtin_amdgcn_sched_group_barrier(0x100, 12, 0);
;     __builtin_amdgcn_sched_group_barrier(0x010, 6, 0);
;     __builtin_amdgcn_sched_group_barrier(0x008, 16, 0);
;     asm volatile("s_waitcnt vmcnt(6) lgkmcnt(0)" ::: "memory");
;     __builtin_amdgcn_s_barrier();
;     asm volatile("" ::: "memory");
;     s0 = (s0 == 2 * STG) ? 0 : s0 + STG;
;     s2 = (s2 == 2 * STG) ? 0 : s2 + STG;
;   }
;   asm volatile("s_waitcnt vmcnt(0)" ::: "memory");
;   __builtin_amdgcn_s_barrier();
;   asm volatile("" ::: "memory");
	s_add_i32 s11, s28, 16
	v_add_u32_e32 v142, s11, v218
	v_add_u32_e32 v150, s11, v0
	v_add_u32_e32 v142, v142, v220
	v_add_u32_e32 v150, v150, v220
	ds_read_b128 v[138:141], v142
	ds_read_b128 v[162:165], v150 offset:8192
	ds_read_b128 v[166:169], v150 offset:10240
	ds_read_b128 v[142:145], v142 offset:2048
	ds_read_b128 v[146:149], v150 offset:12288
	ds_read_b128 v[150:153], v150 offset:14336
	s_waitcnt lgkmcnt(6)
	v_mfma_f32_32x32x16_bf16 v[66:81], v[182:185], v[154:157], v[66:81]
	v_mfma_f32_32x32x16_bf16 v[82:97], v[178:181], v[154:157], v[82:97]
	v_mfma_f32_32x32x16_bf16 v[18:33], v[182:185], v[158:161], v[18:33]
	v_mfma_f32_32x32x16_bf16 v[2:17], v[178:181], v[158:161], v[2:17]
	v_mfma_f32_32x32x16_bf16 v[114:129], v[174:177], v[154:157], v[114:129]
	v_mfma_f32_32x32x16_bf16 v[98:113], v[170:173], v[154:157], v[98:113]
	v_mfma_f32_32x32x16_bf16 v[50:65], v[174:177], v[158:161], v[50:65]
	s_add_i32 s10, s28, 0x6000
	s_cmpk_lg_u32 s28, 0xc000
	s_cselect_b32 s28, s10, 0
	v_mfma_f32_32x32x16_bf16 v[34:49], v[170:173], v[158:161], v[34:49]
	s_add_i32 s11, s28, 16
	s_waitcnt vmcnt(0) lgkmcnt(0)
	s_barrier
	v_add_u32_e32 v158, s11, v218
	v_add_u32_e32 v170, s11, v0
	v_add_u32_e32 v158, v158, v219
	v_add_u32_e32 v170, v170, v219
	ds_read_b128 v[154:157], v158
	ds_read_b128 v[182:185], v170 offset:8192
	ds_read_b128 v[178:181], v170 offset:10240
	ds_read_b128 v[158:161], v158 offset:2048
	ds_read_b128 v[174:177], v170 offset:12288
	ds_read_b128 v[170:173], v170 offset:14336
	v_mfma_f32_32x32x16_bf16 v[66:81], v[162:165], v[138:141], v[66:81]
	v_mfma_f32_32x32x16_bf16 v[82:97], v[166:169], v[138:141], v[82:97]
	v_mfma_f32_32x32x16_bf16 v[18:33], v[162:165], v[142:145], v[18:33]
	v_mfma_f32_32x32x16_bf16 v[2:17], v[166:169], v[142:145], v[2:17]
	v_mfma_f32_32x32x16_bf16 v[114:129], v[146:149], v[138:141], v[114:129]
	v_mfma_f32_32x32x16_bf16 v[98:113], v[150:153], v[138:141], v[98:113]
	v_mfma_f32_32x32x16_bf16 v[50:65], v[146:149], v[142:145], v[50:65]
	v_mfma_f32_32x32x16_bf16 v[34:49], v[150:153], v[142:145], v[34:49]
	s_add_i32 s11, s28, 16
	v_add_u32_e32 v142, s11, v218
	v_add_u32_e32 v150, s11, v0
	v_add_u32_e32 v142, v142, v220
	v_add_u32_e32 v150, v150, v220
	ds_read_b128 v[138:141], v142
	ds_read_b128 v[162:165], v150 offset:8192
	ds_read_b128 v[166:169], v150 offset:10240
	ds_read_b128 v[142:145], v142 offset:2048
	ds_read_b128 v[146:149], v150 offset:12288
	ds_read_b128 v[150:153], v150 offset:14336
	s_waitcnt lgkmcnt(6)
	v_mfma_f32_32x32x16_bf16 v[66:81], v[182:185], v[154:157], v[66:81]
	v_mfma_f32_32x32x16_bf16 v[82:97], v[178:181], v[154:157], v[82:97]
	v_mfma_f32_32x32x16_bf16 v[18:33], v[182:185], v[158:161], v[18:33]
	v_mfma_f32_32x32x16_bf16 v[2:17], v[178:181], v[158:161], v[2:17]
	v_mfma_f32_32x32x16_bf16 v[114:129], v[174:177], v[154:157], v[114:129]
	v_mfma_f32_32x32x16_bf16 v[98:113], v[170:173], v[154:157], v[98:113]
	v_mfma_f32_32x32x16_bf16 v[50:65], v[174:177], v[158:161], v[50:65]
	v_mfma_f32_32x32x16_bf16 v[34:49], v[170:173], v[158:161], v[34:49]
	s_waitcnt lgkmcnt(0)
	v_mfma_f32_32x32x16_bf16 v[66:81], v[162:165], v[138:141], v[66:81]
	v_mfma_f32_32x32x16_bf16 v[82:97], v[166:169], v[138:141], v[82:97]
	v_mfma_f32_32x32x16_bf16 v[18:33], v[162:165], v[142:145], v[18:33]
	v_mfma_f32_32x32x16_bf16 v[2:17], v[166:169], v[142:145], v[2:17]
	v_mfma_f32_32x32x16_bf16 v[114:129], v[146:149], v[138:141], v[114:129]
	v_mfma_f32_32x32x16_bf16 v[98:113], v[150:153], v[138:141], v[98:113]
	v_mfma_f32_32x32x16_bf16 v[50:65], v[146:149], v[142:145], v[50:65]
	v_mfma_f32_32x32x16_bf16 v[34:49], v[150:153], v[142:145], v[34:49]
	s_waitcnt lgkmcnt(0)
	s_setprio 0
	v_mul_lo_u32 v0, v197, s55
	v_add_u32_e32 v0, 16, v0
	s_nop 1
	v_cvt_pk_bf16_f32 v66, v66, v67
	v_cvt_pk_bf16_f32 v67, v68, v69
	v_lshlrev_b32_e32 v68, 3, v196
	s_lshl_b32 s10, s18, 1
	v_add3_u32 v0, v0, v68, s10
	v_cvt_pk_bf16_f32 v68, v70, v71
	v_cvt_pk_bf16_f32 v69, v72, v73
	s_waitcnt vmcnt(0)
	s_barrier
; DI unsigned pk2(float a, float b) { f32x2 v = {a, b}; bf2_t r = __builtin_convertvector(v, bf2_t); return __builtin_bit_cast(unsigned, r); }
;     ...
; #pragma unroll
;     for (int i = 0; i < 2; ++i)
; #pragma unroll
;       for (int j = 0; j < 4; ++j)
; #pragma unroll
;         for (int g = 0; g < 4; ++g) {
;           u32x2 w; w.x = pk2(acc[i][j][4 * g], acc[i][j][4 * g + 1]); w.y = pk2(acc[i][j][4 * g + 2], acc[i][j][4 * g + 3]);
;           *(u32x2*)(smem + (wr * 64 + i * 32 + cl) * 528 + (wc * 128 + j * 32 + 8 * g + 4 * h) * 2) = w;
;         }
;   }
;   __syncthreads();
;     ...
;     const int L = (mt < 512) ? 2048 : 256;
;     const bool first = (m0 % L) == 0, last = ((m0 + 128) % L) == 0;
;     const float* cw = ea.cw; const float* cb = ea.cb;
; #pragma unroll 1
;     for (int p = 0; p < 2; ++p) {
;       const int j8 = (tid2 & 7) * 8;
;       const int ja0 = (nt * 2 + p) * 64, ja = ja0 + j8;
	ds_write2_b64 v0, v[66:67], v[68:69] offset1:2
	v_cvt_pk_bf16_f32 v66, v74, v75
	v_cvt_pk_bf16_f32 v67, v76, v77
	v_cvt_pk_bf16_f32 v68, v78, v79
	v_cvt_pk_bf16_f32 v69, v80, v81
	ds_write2_b64 v0, v[66:67], v[68:69] offset0:4 offset1:6
	v_cvt_pk_bf16_f32 v66, v82, v83
	v_cvt_pk_bf16_f32 v67, v84, v85
	v_cvt_pk_bf16_f32 v68, v86, v87
	v_cvt_pk_bf16_f32 v69, v88, v89
	ds_write2_b64 v0, v[66:67], v[68:69] offset0:8 offset1:10
	v_cvt_pk_bf16_f32 v66, v90, v91
	v_cvt_pk_bf16_f32 v67, v92, v93
	v_cvt_pk_bf16_f32 v68, v94, v95
	v_cvt_pk_bf16_f32 v69, v96, v97
	ds_write2_b64 v0, v[66:67], v[68:69] offset0:12 offset1:14
	v_cvt_pk_bf16_f32 v66, v114, v115
	v_cvt_pk_bf16_f32 v67, v116, v117
	v_cvt_pk_bf16_f32 v68, v118, v119
	v_cvt_pk_bf16_f32 v69, v120, v121
	ds_write2_b64 v0, v[66:67], v[68:69] offset0:16 offset1:18
	v_cvt_pk_bf16_f32 v66, v122, v123
	v_cvt_pk_bf16_f32 v67, v124, v125
	v_cvt_pk_bf16_f32 v68, v126, v127
	v_cvt_pk_bf16_f32 v69, v128, v129
	ds_write2_b64 v0, v[66:67], v[68:69] offset0:20 offset1:22
	v_cvt_pk_bf16_f32 v66, v98, v99
	v_cvt_pk_bf16_f32 v67, v100, v101
	v_cvt_pk_bf16_f32 v68, v102, v103
	v_cvt_pk_bf16_f32 v69, v104, v105
	ds_write2_b64 v0, v[66:67], v[68:69] offset0:24 offset1:26
	v_cvt_pk_bf16_f32 v66, v106, v107
	v_cvt_pk_bf16_f32 v67, v108, v109
	v_cvt_pk_bf16_f32 v68, v110, v111
	v_cvt_pk_bf16_f32 v69, v112, v113
	ds_write2_b64 v0, v[66:67], v[68:69] offset0:28 offset1:30
	v_add_u32_e32 v0, 0x4000, v0
	v_cvt_pk_bf16_f32 v2, v2, v3
	v_cvt_pk_bf16_f32 v3, v4, v5
	v_cvt_pk_bf16_f32 v4, v6, v7
	v_cvt_pk_bf16_f32 v5, v8, v9
	ds_write2_b64 v0, v[2:3], v[4:5] offset0:72 offset1:74
	v_cvt_pk_bf16_f32 v2, v10, v11
	v_cvt_pk_bf16_f32 v3, v12, v13
	v_cvt_pk_bf16_f32 v4, v14, v15
	v_cvt_pk_bf16_f32 v5, v16, v17
	ds_write2_b64 v0, v[2:3], v[4:5] offset0:76 offset1:78
	v_cvt_pk_bf16_f32 v2, v50, v51
	v_cvt_pk_bf16_f32 v3, v52, v53
	v_cvt_pk_bf16_f32 v4, v54, v55
	v_cvt_pk_bf16_f32 v5, v56, v57
	s_cmpk_lt_i32 s15, 0x200
	ds_write2_b64 v0, v[2:3], v[4:5] offset0:80 offset1:82
	v_cvt_pk_bf16_f32 v2, v58, v59
	v_cvt_pk_bf16_f32 v3, v60, v61
	v_cvt_pk_bf16_f32 v4, v62, v63
	v_cvt_pk_bf16_f32 v5, v64, v65
	s_cselect_b32 s10, 0x7ff, s78
	v_cvt_pk_bf16_f32 v18, v18, v19
	v_cvt_pk_bf16_f32 v19, v20, v21
	v_cvt_pk_bf16_f32 v20, v22, v23
	v_cvt_pk_bf16_f32 v21, v24, v25
	ds_write2_b64 v0, v[2:3], v[4:5] offset0:84 offset1:86
	v_cvt_pk_bf16_f32 v2, v34, v35
	v_cvt_pk_bf16_f32 v3, v36, v37
	v_cvt_pk_bf16_f32 v4, v38, v39
	v_cvt_pk_bf16_f32 v5, v40, v41
	s_and_b32 s11, s10, s46
	ds_write2_b64 v0, v[18:19], v[20:21] offset0:64 offset1:66
	v_cvt_pk_bf16_f32 v18, v26, v27
	v_cvt_pk_bf16_f32 v19, v28, v29
	v_cvt_pk_bf16_f32 v20, v30, v31
	v_cvt_pk_bf16_f32 v21, v32, v33
	ds_write2_b64 v0, v[2:3], v[4:5] offset0:88 offset1:90
	v_cvt_pk_bf16_f32 v2, v42, v43
	v_cvt_pk_bf16_f32 v3, v44, v45
	v_cvt_pk_bf16_f32 v4, v46, v47
	v_cvt_pk_bf16_f32 v5, v48, v49
	s_cmp_eq_u32 s11, 0
	ds_write2_b64 v0, v[18:19], v[20:21] offset0:68 offset1:70
	ds_write2_b64 v0, v[2:3], v[4:5] offset0:92 offset1:94
	s_waitcnt vmcnt(0) lgkmcnt(0)
	s_barrier
	s_cselect_b64 s[18:19], -1, 0
	s_add_i32 s11, s46, 0x80
	v_lshlrev_b32_e32 v0, 3, v189
	s_and_b32 s10, s11, s10
	v_and_b32_e32 v96, 56, v0
	s_cmp_eq_u32 s10, 0
	v_lshlrev_b32_e32 v0, 1, v96
	s_mov_b32 s40, 0
	s_cselect_b64 s[20:21], -1, 0
	s_lshl_b32 s47, s22, 7
	v_add_u32_e32 v97, 16, v0
	v_lshl_add_u64 v[90:91], s[44:45], 0, v[0:1]
	s_mov_b64 s[28:29], -1
	s_branch .LBB0_275
